# P4 loop: row loads two rows ahead (four register buffers, fully unrolled)
# baseline (speedup 1.0000x reference)
; DI unsigned cvtpk(float lo, float hi) { unsigned r; asm volatile("v_cvt_pk_bf16_f32 %0, %1, %2" : "=v"(r) : "v"(lo), "v"(hi)); return r; }
; DI float bflo(unsigned w) { return __uint_as_float(w << 16); }
; DI float bfhi(unsigned w) { return __uint_as_float(w & 0xffff0000u); }
; DI float sigm(float x) { return rcpf_(1.f + ex2(-x * LOG2E)); }
; DI float ub(unsigned w, int i) { return (float)((w >> (8 * i)) & 0xffu); }
; DI void phase_fixup(const Params& p) {
;     ...
;     for (int it = blockIdx.x; it < 512; it += gridDim.x) {
;         const int c = it >> 2, rq = it & 3;
;         float cf[8], cb[8];
;         { const f32x4 a0 = *(const f32x4*)(CAR + (size_t)c * 2048 + ch), a1 = *(const f32x4*)(CAR + (size_t)c * 2048 + ch + 4);
;           const f32x4 b0 = *(const f32x4*)(CAR + (size_t)(128 + c) * 2048 + ch), b1 = *(const f32x4*)(CAR + (size_t)(128 + c) * 2048 + ch + 4);
; #pragma unroll
;           for (int i = 0; i < 4; ++i) { cf[i] = a0[i] * (1.f / 255.f); cf[4 + i] = a1[i] * (1.f / 255.f); cb[i] = b0[i] * (1.f / 255.f); cb[4 + i] = b1[i] * (1.f / 255.f); } }
; #pragma unroll 8
;         for (int i = 0; i < 16; ++i) {
;             const size_t off = (size_t)(c * 128 + rq * 32 + 2 * i + r2) * 2048 + ch;
;             const u32x4 g = __builtin_nontemporal_load((const u32x4*)(ZG + off)), h = __builtin_nontemporal_load((const u32x4*)(HLp + off)), pp = __builtin_nontemporal_load((const u32x4*)(PPp + off));
;             u32x4 o;
; #pragma unroll
;             for (int k = 0; k < 4; ++k) {
;                 const float g0 = bflo(g[k]), g1 = bfhi(g[k]);
;                 const float y0 = (bflo(h[k]) + ub(pp[k], 0) * cf[2 * k] + ub(pp[k], 1) * cb[2 * k]) * g0 * sigm(g0);
;                 const float y1 = (bfhi(h[k]) + ub(pp[k], 2) * cf[2 * k + 1] + ub(pp[k], 3) * cb[2 * k + 1]) * g1 * sigm(g1);
;                 o[k] = cvtpk(y0, y1);
;             }
;             *(u32x4*)(ZG + off) = o;
;         }
.LBB0_377:
	s_ashr_i32 s20, s17, 2
	s_ashr_i32 s21, s20, 31
	s_lshl_b64 s[18:19], s[20:21], 13
	v_lshl_add_u64 v[2:3], v[0:1], 0, s[18:19]
	v_add_co_u32_e32 v12, vcc, 0x100000, v2
	global_load_dwordx4 v[14:17], v[2:3], off offset:16
	global_load_dwordx4 v[18:21], v[2:3], off
	v_addc_co_u32_e32 v13, vcc, 0, v3, vcc
	v_lshl_add_u64 v[10:11], v[2:3], 0, s[6:7]
	global_load_dwordx4 v[2:5], v[12:13], off
	global_load_dwordx4 v[6:9], v[10:11], off offset:16
	s_and_b32 s19, s15, 0x60
	v_lshl_or_b32 v26, s20, 7, v50
	s_mov_b32 s18, 0
	v_or_b32_e32 v52, s19, v26
	v_lshl_or_b32 v22, v52, 12, v51
	s_mov_b32 s40, 0xbfb8aa3b
	v_mov_b32_e32 v70, v22
	global_load_dwordx4 v[28:31], v70, s[10:11]
	global_load_dwordx4 v[32:35], v70, s[4:5]
	global_load_dwordx4 v[36:39], v70, s[12:13]
	v_add_u32_e32 v71, 0x2000, v22
	global_load_dwordx4 v[54:57], v71, s[10:11]
	global_load_dwordx4 v[58:61], v71, s[4:5]
	global_load_dwordx4 v[62:65], v71, s[12:13]
	s_waitcnt vmcnt(6)
	v_pk_mul_f32 v[18:19], v[18:19], s[14:15] op_sel_hi:[1,0]
	v_pk_mul_f32 v[20:21], v[20:21], s[14:15] op_sel_hi:[1,0]
	v_pk_mul_f32 v[14:15], v[14:15], s[14:15] op_sel_hi:[1,0]
	v_pk_mul_f32 v[16:17], v[16:17], s[14:15] op_sel_hi:[1,0]
	v_pk_mul_f32 v[2:3], v[2:3], s[14:15] op_sel_hi:[1,0]
	v_pk_mul_f32 v[4:5], v[4:5], s[14:15] op_sel_hi:[1,0]
	v_pk_mul_f32 v[6:7], v[6:7], s[14:15] op_sel_hi:[1,0]
	v_pk_mul_f32 v[8:9], v[8:9], s[14:15] op_sel_hi:[1,0]
	v_add_u32_e32 v128, 0x4000, v22
	global_load_dwordx4 v[112:115], v128, s[10:11]
	global_load_dwordx4 v[116:119], v128, s[4:5]
	global_load_dwordx4 v[120:123], v128, s[12:13]
	s_waitcnt vmcnt(6)
	v_lshlrev_b32_e32 v72, 16, v28
	v_and_b32_e32 v73, 0xffff0000, v28
	v_lshlrev_b32_e32 v80, 16, v32
	v_and_b32_e32 v81, 0xffff0000, v32
	v_cvt_f32_ubyte0_e32 v88, v36
	v_cvt_f32_ubyte2_e32 v89, v36
	v_cvt_f32_ubyte1_e32 v96, v36
	v_cvt_f32_ubyte3_e32 v97, v36
	v_lshlrev_b32_e32 v74, 16, v29
	v_and_b32_e32 v75, 0xffff0000, v29
	v_lshlrev_b32_e32 v82, 16, v33
	v_and_b32_e32 v83, 0xffff0000, v33
	v_cvt_f32_ubyte0_e32 v90, v37
	v_cvt_f32_ubyte2_e32 v91, v37
	v_cvt_f32_ubyte1_e32 v98, v37
	v_cvt_f32_ubyte3_e32 v99, v37
	v_lshlrev_b32_e32 v76, 16, v30
	v_and_b32_e32 v77, 0xffff0000, v30
	v_lshlrev_b32_e32 v84, 16, v34
	v_and_b32_e32 v85, 0xffff0000, v34
	v_cvt_f32_ubyte0_e32 v92, v38
	v_cvt_f32_ubyte2_e32 v93, v38
	v_cvt_f32_ubyte1_e32 v100, v38
	v_cvt_f32_ubyte3_e32 v101, v38
	v_lshlrev_b32_e32 v78, 16, v31
	v_and_b32_e32 v79, 0xffff0000, v31
	v_lshlrev_b32_e32 v86, 16, v35
	v_and_b32_e32 v87, 0xffff0000, v35
	v_cvt_f32_ubyte0_e32 v94, v39
	v_cvt_f32_ubyte2_e32 v95, v39
	v_cvt_f32_ubyte1_e32 v102, v39
	v_cvt_f32_ubyte3_e32 v103, v39
	v_pk_mul_f32 v[104:105], v[72:73], s[40:41] op_sel_hi:[1,0]
	v_pk_mul_f32 v[106:107], v[74:75], s[40:41] op_sel_hi:[1,0]
	v_pk_mul_f32 v[108:109], v[76:77], s[40:41] op_sel_hi:[1,0]
	v_pk_mul_f32 v[110:111], v[78:79], s[40:41] op_sel_hi:[1,0]
	v_pk_fma_f32 v[80:81], v[88:89], v[18:19], v[80:81]
	v_pk_fma_f32 v[82:83], v[90:91], v[20:21], v[82:83]
	v_pk_fma_f32 v[84:85], v[92:93], v[14:15], v[84:85]
	v_pk_fma_f32 v[86:87], v[94:95], v[16:17], v[86:87]
	v_exp_f32_e32 v104, v104
	v_exp_f32_e32 v105, v105
	v_exp_f32_e32 v106, v106
	v_exp_f32_e32 v107, v107
	v_exp_f32_e32 v108, v108
	v_exp_f32_e32 v109, v109
	v_exp_f32_e32 v110, v110
	v_exp_f32_e32 v111, v111
	v_pk_fma_f32 v[80:81], v[96:97], v[2:3], v[80:81]
	v_pk_fma_f32 v[82:83], v[98:99], v[4:5], v[82:83]
	v_pk_fma_f32 v[84:85], v[100:101], v[6:7], v[84:85]
	v_pk_fma_f32 v[86:87], v[102:103], v[8:9], v[86:87]
	v_pk_add_f32 v[104:105], v[104:105], 1.0 op_sel_hi:[1,0]
	v_pk_add_f32 v[106:107], v[106:107], 1.0 op_sel_hi:[1,0]
	v_pk_add_f32 v[108:109], v[108:109], 1.0 op_sel_hi:[1,0]
	v_pk_add_f32 v[110:111], v[110:111], 1.0 op_sel_hi:[1,0]
	v_rcp_f32_e32 v104, v104
	v_rcp_f32_e32 v105, v105
	v_rcp_f32_e32 v106, v106
	v_rcp_f32_e32 v107, v107
	v_rcp_f32_e32 v108, v108
	v_rcp_f32_e32 v109, v109
	v_rcp_f32_e32 v110, v110
	v_rcp_f32_e32 v111, v111
	v_pk_mul_f32 v[80:81], v[80:81], v[72:73]
	v_pk_mul_f32 v[82:83], v[82:83], v[74:75]
	v_pk_mul_f32 v[84:85], v[84:85], v[76:77]
	v_pk_mul_f32 v[86:87], v[86:87], v[78:79]
	v_pk_mul_f32 v[80:81], v[104:105], v[80:81]
	v_pk_mul_f32 v[82:83], v[106:107], v[82:83]
	v_pk_mul_f32 v[84:85], v[108:109], v[84:85]
	v_pk_mul_f32 v[86:87], v[110:111], v[86:87]
	v_cvt_pk_bf16_f32 v24, v80, v81
	v_cvt_pk_bf16_f32 v25, v82, v83
	v_cvt_pk_bf16_f32 v26, v84, v85
	v_cvt_pk_bf16_f32 v27, v86, v87
	global_store_dwordx4 v70, v[24:27], s[10:11]
	v_add_u32_e32 v129, 0x6000, v22
	global_load_dwordx4 v[132:135], v129, s[10:11]
	global_load_dwordx4 v[136:139], v129, s[4:5]
	global_load_dwordx4 v[140:143], v129, s[12:13]
	s_waitcnt vmcnt(7)
; DI unsigned cvtpk(float lo, float hi) { unsigned r; asm volatile("v_cvt_pk_bf16_f32 %0, %1, %2" : "=v"(r) : "v"(lo), "v"(hi)); return r; }
; DI float bflo(unsigned w) { return __uint_as_float(w << 16); }
; DI float bfhi(unsigned w) { return __uint_as_float(w & 0xffff0000u); }
; DI float sigm(float x) { return rcpf_(1.f + ex2(-x * LOG2E)); }
; DI float ub(unsigned w, int i) { return (float)((w >> (8 * i)) & 0xffu); }
; DI void phase_fixup(const Params& p) {
;     ...
;         for (int i = 0; i < 16; ++i) {
;             const size_t off = (size_t)(c * 128 + rq * 32 + 2 * i + r2) * 2048 + ch;
;             const u32x4 g = __builtin_nontemporal_load((const u32x4*)(ZG + off)), h = __builtin_nontemporal_load((const u32x4*)(HLp + off)), pp = __builtin_nontemporal_load((const u32x4*)(PPp + off));
;             u32x4 o;
; #pragma unroll
;             for (int k = 0; k < 4; ++k) {
;                 const float g0 = bflo(g[k]), g1 = bfhi(g[k]);
;                 const float y0 = (bflo(h[k]) + ub(pp[k], 0) * cf[2 * k] + ub(pp[k], 1) * cb[2 * k]) * g0 * sigm(g0);
;                 const float y1 = (bfhi(h[k]) + ub(pp[k], 2) * cf[2 * k + 1] + ub(pp[k], 3) * cb[2 * k + 1]) * g1 * sigm(g1);
;                 o[k] = cvtpk(y0, y1);
;             }
;             *(u32x4*)(ZG + off) = o;
;         }
	v_lshlrev_b32_e32 v72, 16, v54
	v_and_b32_e32 v73, 0xffff0000, v54
	v_lshlrev_b32_e32 v80, 16, v58
	v_and_b32_e32 v81, 0xffff0000, v58
	v_cvt_f32_ubyte0_e32 v88, v62
	v_cvt_f32_ubyte2_e32 v89, v62
	v_cvt_f32_ubyte1_e32 v96, v62
	v_cvt_f32_ubyte3_e32 v97, v62
	v_lshlrev_b32_e32 v74, 16, v55
	v_and_b32_e32 v75, 0xffff0000, v55
	v_lshlrev_b32_e32 v82, 16, v59
	v_and_b32_e32 v83, 0xffff0000, v59
	v_cvt_f32_ubyte0_e32 v90, v63
	v_cvt_f32_ubyte2_e32 v91, v63
	v_cvt_f32_ubyte1_e32 v98, v63
	v_cvt_f32_ubyte3_e32 v99, v63
	v_lshlrev_b32_e32 v76, 16, v56
	v_and_b32_e32 v77, 0xffff0000, v56
	v_lshlrev_b32_e32 v84, 16, v60
	v_and_b32_e32 v85, 0xffff0000, v60
	v_cvt_f32_ubyte0_e32 v92, v64
	v_cvt_f32_ubyte2_e32 v93, v64
	v_cvt_f32_ubyte1_e32 v100, v64
	v_cvt_f32_ubyte3_e32 v101, v64
	v_lshlrev_b32_e32 v78, 16, v57
	v_and_b32_e32 v79, 0xffff0000, v57
	v_lshlrev_b32_e32 v86, 16, v61
	v_and_b32_e32 v87, 0xffff0000, v61
	v_cvt_f32_ubyte0_e32 v94, v65
	v_cvt_f32_ubyte2_e32 v95, v65
	v_cvt_f32_ubyte1_e32 v102, v65
	v_cvt_f32_ubyte3_e32 v103, v65
	v_pk_mul_f32 v[104:105], v[72:73], s[40:41] op_sel_hi:[1,0]
	v_pk_mul_f32 v[106:107], v[74:75], s[40:41] op_sel_hi:[1,0]
	v_pk_mul_f32 v[108:109], v[76:77], s[40:41] op_sel_hi:[1,0]
	v_pk_mul_f32 v[110:111], v[78:79], s[40:41] op_sel_hi:[1,0]
	v_pk_fma_f32 v[80:81], v[88:89], v[18:19], v[80:81]
	v_pk_fma_f32 v[82:83], v[90:91], v[20:21], v[82:83]
	v_pk_fma_f32 v[84:85], v[92:93], v[14:15], v[84:85]
	v_pk_fma_f32 v[86:87], v[94:95], v[16:17], v[86:87]
	v_exp_f32_e32 v104, v104
	v_exp_f32_e32 v105, v105
	v_exp_f32_e32 v106, v106
	v_exp_f32_e32 v107, v107
	v_exp_f32_e32 v108, v108
	v_exp_f32_e32 v109, v109
	v_exp_f32_e32 v110, v110
	v_exp_f32_e32 v111, v111
	v_pk_fma_f32 v[80:81], v[96:97], v[2:3], v[80:81]
	v_pk_fma_f32 v[82:83], v[98:99], v[4:5], v[82:83]
	v_pk_fma_f32 v[84:85], v[100:101], v[6:7], v[84:85]
	v_pk_fma_f32 v[86:87], v[102:103], v[8:9], v[86:87]
	v_pk_add_f32 v[104:105], v[104:105], 1.0 op_sel_hi:[1,0]
	v_pk_add_f32 v[106:107], v[106:107], 1.0 op_sel_hi:[1,0]
	v_pk_add_f32 v[108:109], v[108:109], 1.0 op_sel_hi:[1,0]
	v_pk_add_f32 v[110:111], v[110:111], 1.0 op_sel_hi:[1,0]
	v_rcp_f32_e32 v104, v104
	v_rcp_f32_e32 v105, v105
	v_rcp_f32_e32 v106, v106
	v_rcp_f32_e32 v107, v107
	v_rcp_f32_e32 v108, v108
	v_rcp_f32_e32 v109, v109
	v_rcp_f32_e32 v110, v110
	v_rcp_f32_e32 v111, v111
	v_pk_mul_f32 v[80:81], v[80:81], v[72:73]
	v_pk_mul_f32 v[82:83], v[82:83], v[74:75]
	v_pk_mul_f32 v[84:85], v[84:85], v[76:77]
	v_pk_mul_f32 v[86:87], v[86:87], v[78:79]
	v_pk_mul_f32 v[80:81], v[104:105], v[80:81]
	v_pk_mul_f32 v[82:83], v[106:107], v[82:83]
	v_pk_mul_f32 v[84:85], v[108:109], v[84:85]
	v_pk_mul_f32 v[86:87], v[110:111], v[86:87]
	v_cvt_pk_bf16_f32 v66, v80, v81
	v_cvt_pk_bf16_f32 v67, v82, v83
	v_cvt_pk_bf16_f32 v68, v84, v85
	v_cvt_pk_bf16_f32 v69, v86, v87
	global_store_dwordx4 v71, v[66:69], s[10:11]
	v_add_u32_e32 v70, 0x8000, v22
	global_load_dwordx4 v[28:31], v70, s[10:11]
	global_load_dwordx4 v[32:35], v70, s[4:5]
	global_load_dwordx4 v[36:39], v70, s[12:13]
	s_waitcnt vmcnt(8)
	v_lshlrev_b32_e32 v72, 16, v112
	v_and_b32_e32 v73, 0xffff0000, v112
	v_lshlrev_b32_e32 v80, 16, v116
	v_and_b32_e32 v81, 0xffff0000, v116
	v_cvt_f32_ubyte0_e32 v88, v120
	v_cvt_f32_ubyte2_e32 v89, v120
	v_cvt_f32_ubyte1_e32 v96, v120
	v_cvt_f32_ubyte3_e32 v97, v120
	v_lshlrev_b32_e32 v74, 16, v113
	v_and_b32_e32 v75, 0xffff0000, v113
	v_lshlrev_b32_e32 v82, 16, v117
	v_and_b32_e32 v83, 0xffff0000, v117
	v_cvt_f32_ubyte0_e32 v90, v121
	v_cvt_f32_ubyte2_e32 v91, v121
	v_cvt_f32_ubyte1_e32 v98, v121
	v_cvt_f32_ubyte3_e32 v99, v121
	v_lshlrev_b32_e32 v76, 16, v114
	v_and_b32_e32 v77, 0xffff0000, v114
	v_lshlrev_b32_e32 v84, 16, v118
	v_and_b32_e32 v85, 0xffff0000, v118
	v_cvt_f32_ubyte0_e32 v92, v122
	v_cvt_f32_ubyte2_e32 v93, v122
	v_cvt_f32_ubyte1_e32 v100, v122
	v_cvt_f32_ubyte3_e32 v101, v122
	v_lshlrev_b32_e32 v78, 16, v115
	v_and_b32_e32 v79, 0xffff0000, v115
	v_lshlrev_b32_e32 v86, 16, v119
	v_and_b32_e32 v87, 0xffff0000, v119
	v_cvt_f32_ubyte0_e32 v94, v123
	v_cvt_f32_ubyte2_e32 v95, v123
	v_cvt_f32_ubyte1_e32 v102, v123
	v_cvt_f32_ubyte3_e32 v103, v123
	v_pk_mul_f32 v[104:105], v[72:73], s[40:41] op_sel_hi:[1,0]
	v_pk_mul_f32 v[106:107], v[74:75], s[40:41] op_sel_hi:[1,0]
	v_pk_mul_f32 v[108:109], v[76:77], s[40:41] op_sel_hi:[1,0]
	v_pk_mul_f32 v[110:111], v[78:79], s[40:41] op_sel_hi:[1,0]
	v_pk_fma_f32 v[80:81], v[88:89], v[18:19], v[80:81]
	v_pk_fma_f32 v[82:83], v[90:91], v[20:21], v[82:83]
	v_pk_fma_f32 v[84:85], v[92:93], v[14:15], v[84:85]
	v_pk_fma_f32 v[86:87], v[94:95], v[16:17], v[86:87]
	v_exp_f32_e32 v104, v104
	v_exp_f32_e32 v105, v105
	v_exp_f32_e32 v106, v106
	v_exp_f32_e32 v107, v107
	v_exp_f32_e32 v108, v108
	v_exp_f32_e32 v109, v109
	v_exp_f32_e32 v110, v110
	v_exp_f32_e32 v111, v111
	v_pk_fma_f32 v[80:81], v[96:97], v[2:3], v[80:81]
	v_pk_fma_f32 v[82:83], v[98:99], v[4:5], v[82:83]
	v_pk_fma_f32 v[84:85], v[100:101], v[6:7], v[84:85]
	v_pk_fma_f32 v[86:87], v[102:103], v[8:9], v[86:87]
	v_pk_add_f32 v[104:105], v[104:105], 1.0 op_sel_hi:[1,0]
	v_pk_add_f32 v[106:107], v[106:107], 1.0 op_sel_hi:[1,0]
	v_pk_add_f32 v[108:109], v[108:109], 1.0 op_sel_hi:[1,0]
	v_pk_add_f32 v[110:111], v[110:111], 1.0 op_sel_hi:[1,0]
	v_rcp_f32_e32 v104, v104
	v_rcp_f32_e32 v105, v105
	v_rcp_f32_e32 v106, v106
	v_rcp_f32_e32 v107, v107
	v_rcp_f32_e32 v108, v108
	v_rcp_f32_e32 v109, v109
	v_rcp_f32_e32 v110, v110
	v_rcp_f32_e32 v111, v111
	v_pk_mul_f32 v[80:81], v[80:81], v[72:73]
	v_pk_mul_f32 v[82:83], v[82:83], v[74:75]
	v_pk_mul_f32 v[84:85], v[84:85], v[76:77]
	v_pk_mul_f32 v[86:87], v[86:87], v[78:79]
	v_pk_mul_f32 v[80:81], v[104:105], v[80:81]
	v_pk_mul_f32 v[82:83], v[106:107], v[82:83]
	v_pk_mul_f32 v[84:85], v[108:109], v[84:85]
	v_pk_mul_f32 v[86:87], v[110:111], v[86:87]
	v_cvt_pk_bf16_f32 v124, v80, v81
	v_cvt_pk_bf16_f32 v125, v82, v83
	v_cvt_pk_bf16_f32 v126, v84, v85
	v_cvt_pk_bf16_f32 v127, v86, v87
	global_store_dwordx4 v128, v[124:127], s[10:11]
	v_add_u32_e32 v71, 0xa000, v22
	global_load_dwordx4 v[54:57], v71, s[10:11]
	global_load_dwordx4 v[58:61], v71, s[4:5]
	global_load_dwordx4 v[62:65], v71, s[12:13]
	s_waitcnt vmcnt(8)
; DI unsigned cvtpk(float lo, float hi) { unsigned r; asm volatile("v_cvt_pk_bf16_f32 %0, %1, %2" : "=v"(r) : "v"(lo), "v"(hi)); return r; }
; DI float bflo(unsigned w) { return __uint_as_float(w << 16); }
; DI float bfhi(unsigned w) { return __uint_as_float(w & 0xffff0000u); }
; DI float sigm(float x) { return rcpf_(1.f + ex2(-x * LOG2E)); }
; DI float ub(unsigned w, int i) { return (float)((w >> (8 * i)) & 0xffu); }
; DI void phase_fixup(const Params& p) {
;     ...
;         for (int i = 0; i < 16; ++i) {
;             const size_t off = (size_t)(c * 128 + rq * 32 + 2 * i + r2) * 2048 + ch;
;             const u32x4 g = __builtin_nontemporal_load((const u32x4*)(ZG + off)), h = __builtin_nontemporal_load((const u32x4*)(HLp + off)), pp = __builtin_nontemporal_load((const u32x4*)(PPp + off));
;             u32x4 o;
; #pragma unroll
;             for (int k = 0; k < 4; ++k) {
;                 const float g0 = bflo(g[k]), g1 = bfhi(g[k]);
;                 const float y0 = (bflo(h[k]) + ub(pp[k], 0) * cf[2 * k] + ub(pp[k], 1) * cb[2 * k]) * g0 * sigm(g0);
;                 const float y1 = (bfhi(h[k]) + ub(pp[k], 2) * cf[2 * k + 1] + ub(pp[k], 3) * cb[2 * k + 1]) * g1 * sigm(g1);
;                 o[k] = cvtpk(y0, y1);
;             }
;             *(u32x4*)(ZG + off) = o;
;         }
	v_lshlrev_b32_e32 v72, 16, v132
	v_and_b32_e32 v73, 0xffff0000, v132
	v_lshlrev_b32_e32 v80, 16, v136
	v_and_b32_e32 v81, 0xffff0000, v136
	v_cvt_f32_ubyte0_e32 v88, v140
	v_cvt_f32_ubyte2_e32 v89, v140
	v_cvt_f32_ubyte1_e32 v96, v140
	v_cvt_f32_ubyte3_e32 v97, v140
	v_lshlrev_b32_e32 v74, 16, v133
	v_and_b32_e32 v75, 0xffff0000, v133
	v_lshlrev_b32_e32 v82, 16, v137
	v_and_b32_e32 v83, 0xffff0000, v137
	v_cvt_f32_ubyte0_e32 v90, v141
	v_cvt_f32_ubyte2_e32 v91, v141
	v_cvt_f32_ubyte1_e32 v98, v141
	v_cvt_f32_ubyte3_e32 v99, v141
	v_lshlrev_b32_e32 v76, 16, v134
	v_and_b32_e32 v77, 0xffff0000, v134
	v_lshlrev_b32_e32 v84, 16, v138
	v_and_b32_e32 v85, 0xffff0000, v138
	v_cvt_f32_ubyte0_e32 v92, v142
	v_cvt_f32_ubyte2_e32 v93, v142
	v_cvt_f32_ubyte1_e32 v100, v142
	v_cvt_f32_ubyte3_e32 v101, v142
	v_lshlrev_b32_e32 v78, 16, v135
	v_and_b32_e32 v79, 0xffff0000, v135
	v_lshlrev_b32_e32 v86, 16, v139
	v_and_b32_e32 v87, 0xffff0000, v139
	v_cvt_f32_ubyte0_e32 v94, v143
	v_cvt_f32_ubyte2_e32 v95, v143
	v_cvt_f32_ubyte1_e32 v102, v143
	v_cvt_f32_ubyte3_e32 v103, v143
	v_pk_mul_f32 v[104:105], v[72:73], s[40:41] op_sel_hi:[1,0]
	v_pk_mul_f32 v[106:107], v[74:75], s[40:41] op_sel_hi:[1,0]
	v_pk_mul_f32 v[108:109], v[76:77], s[40:41] op_sel_hi:[1,0]
	v_pk_mul_f32 v[110:111], v[78:79], s[40:41] op_sel_hi:[1,0]
	v_pk_fma_f32 v[80:81], v[88:89], v[18:19], v[80:81]
	v_pk_fma_f32 v[82:83], v[90:91], v[20:21], v[82:83]
	v_pk_fma_f32 v[84:85], v[92:93], v[14:15], v[84:85]
	v_pk_fma_f32 v[86:87], v[94:95], v[16:17], v[86:87]
	v_exp_f32_e32 v104, v104
	v_exp_f32_e32 v105, v105
	v_exp_f32_e32 v106, v106
	v_exp_f32_e32 v107, v107
	v_exp_f32_e32 v108, v108
	v_exp_f32_e32 v109, v109
	v_exp_f32_e32 v110, v110
	v_exp_f32_e32 v111, v111
	v_pk_fma_f32 v[80:81], v[96:97], v[2:3], v[80:81]
	v_pk_fma_f32 v[82:83], v[98:99], v[4:5], v[82:83]
	v_pk_fma_f32 v[84:85], v[100:101], v[6:7], v[84:85]
	v_pk_fma_f32 v[86:87], v[102:103], v[8:9], v[86:87]
	v_pk_add_f32 v[104:105], v[104:105], 1.0 op_sel_hi:[1,0]
	v_pk_add_f32 v[106:107], v[106:107], 1.0 op_sel_hi:[1,0]
	v_pk_add_f32 v[108:109], v[108:109], 1.0 op_sel_hi:[1,0]
	v_pk_add_f32 v[110:111], v[110:111], 1.0 op_sel_hi:[1,0]
	v_rcp_f32_e32 v104, v104
	v_rcp_f32_e32 v105, v105
	v_rcp_f32_e32 v106, v106
	v_rcp_f32_e32 v107, v107
	v_rcp_f32_e32 v108, v108
	v_rcp_f32_e32 v109, v109
	v_rcp_f32_e32 v110, v110
	v_rcp_f32_e32 v111, v111
	v_pk_mul_f32 v[80:81], v[80:81], v[72:73]
	v_pk_mul_f32 v[82:83], v[82:83], v[74:75]
	v_pk_mul_f32 v[84:85], v[84:85], v[76:77]
	v_pk_mul_f32 v[86:87], v[86:87], v[78:79]
	v_pk_mul_f32 v[80:81], v[104:105], v[80:81]
	v_pk_mul_f32 v[82:83], v[106:107], v[82:83]
	v_pk_mul_f32 v[84:85], v[108:109], v[84:85]
	v_pk_mul_f32 v[86:87], v[110:111], v[86:87]
	v_cvt_pk_bf16_f32 v144, v80, v81
	v_cvt_pk_bf16_f32 v145, v82, v83
	v_cvt_pk_bf16_f32 v146, v84, v85
	v_cvt_pk_bf16_f32 v147, v86, v87
	global_store_dwordx4 v129, v[144:147], s[10:11]
	v_add_u32_e32 v128, 0xc000, v22
	global_load_dwordx4 v[112:115], v128, s[10:11]
	global_load_dwordx4 v[116:119], v128, s[4:5]
	global_load_dwordx4 v[120:123], v128, s[12:13]
	s_waitcnt vmcnt(8)
	v_lshlrev_b32_e32 v72, 16, v28
	v_and_b32_e32 v73, 0xffff0000, v28
	v_lshlrev_b32_e32 v80, 16, v32
	v_and_b32_e32 v81, 0xffff0000, v32
	v_cvt_f32_ubyte0_e32 v88, v36
	v_cvt_f32_ubyte2_e32 v89, v36
	v_cvt_f32_ubyte1_e32 v96, v36
	v_cvt_f32_ubyte3_e32 v97, v36
	v_lshlrev_b32_e32 v74, 16, v29
	v_and_b32_e32 v75, 0xffff0000, v29
	v_lshlrev_b32_e32 v82, 16, v33
	v_and_b32_e32 v83, 0xffff0000, v33
	v_cvt_f32_ubyte0_e32 v90, v37
	v_cvt_f32_ubyte2_e32 v91, v37
	v_cvt_f32_ubyte1_e32 v98, v37
	v_cvt_f32_ubyte3_e32 v99, v37
	v_lshlrev_b32_e32 v76, 16, v30
	v_and_b32_e32 v77, 0xffff0000, v30
	v_lshlrev_b32_e32 v84, 16, v34
	v_and_b32_e32 v85, 0xffff0000, v34
	v_cvt_f32_ubyte0_e32 v92, v38
	v_cvt_f32_ubyte2_e32 v93, v38
	v_cvt_f32_ubyte1_e32 v100, v38
	v_cvt_f32_ubyte3_e32 v101, v38
	v_lshlrev_b32_e32 v78, 16, v31
	v_and_b32_e32 v79, 0xffff0000, v31
	v_lshlrev_b32_e32 v86, 16, v35
	v_and_b32_e32 v87, 0xffff0000, v35
	v_cvt_f32_ubyte0_e32 v94, v39
	v_cvt_f32_ubyte2_e32 v95, v39
	v_cvt_f32_ubyte1_e32 v102, v39
	v_cvt_f32_ubyte3_e32 v103, v39
	v_pk_mul_f32 v[104:105], v[72:73], s[40:41] op_sel_hi:[1,0]
	v_pk_mul_f32 v[106:107], v[74:75], s[40:41] op_sel_hi:[1,0]
	v_pk_mul_f32 v[108:109], v[76:77], s[40:41] op_sel_hi:[1,0]
	v_pk_mul_f32 v[110:111], v[78:79], s[40:41] op_sel_hi:[1,0]
	v_pk_fma_f32 v[80:81], v[88:89], v[18:19], v[80:81]
	v_pk_fma_f32 v[82:83], v[90:91], v[20:21], v[82:83]
	v_pk_fma_f32 v[84:85], v[92:93], v[14:15], v[84:85]
	v_pk_fma_f32 v[86:87], v[94:95], v[16:17], v[86:87]
	v_exp_f32_e32 v104, v104
	v_exp_f32_e32 v105, v105
	v_exp_f32_e32 v106, v106
	v_exp_f32_e32 v107, v107
	v_exp_f32_e32 v108, v108
	v_exp_f32_e32 v109, v109
	v_exp_f32_e32 v110, v110
	v_exp_f32_e32 v111, v111
	v_pk_fma_f32 v[80:81], v[96:97], v[2:3], v[80:81]
	v_pk_fma_f32 v[82:83], v[98:99], v[4:5], v[82:83]
	v_pk_fma_f32 v[84:85], v[100:101], v[6:7], v[84:85]
	v_pk_fma_f32 v[86:87], v[102:103], v[8:9], v[86:87]
	v_pk_add_f32 v[104:105], v[104:105], 1.0 op_sel_hi:[1,0]
	v_pk_add_f32 v[106:107], v[106:107], 1.0 op_sel_hi:[1,0]
	v_pk_add_f32 v[108:109], v[108:109], 1.0 op_sel_hi:[1,0]
	v_pk_add_f32 v[110:111], v[110:111], 1.0 op_sel_hi:[1,0]
	v_rcp_f32_e32 v104, v104
	v_rcp_f32_e32 v105, v105
	v_rcp_f32_e32 v106, v106
	v_rcp_f32_e32 v107, v107
	v_rcp_f32_e32 v108, v108
	v_rcp_f32_e32 v109, v109
	v_rcp_f32_e32 v110, v110
	v_rcp_f32_e32 v111, v111
	v_pk_mul_f32 v[80:81], v[80:81], v[72:73]
	v_pk_mul_f32 v[82:83], v[82:83], v[74:75]
	v_pk_mul_f32 v[84:85], v[84:85], v[76:77]
	v_pk_mul_f32 v[86:87], v[86:87], v[78:79]
	v_pk_mul_f32 v[80:81], v[104:105], v[80:81]
	v_pk_mul_f32 v[82:83], v[106:107], v[82:83]
	v_pk_mul_f32 v[84:85], v[108:109], v[84:85]
	v_pk_mul_f32 v[86:87], v[110:111], v[86:87]
	v_cvt_pk_bf16_f32 v24, v80, v81
	v_cvt_pk_bf16_f32 v25, v82, v83
	v_cvt_pk_bf16_f32 v26, v84, v85
	v_cvt_pk_bf16_f32 v27, v86, v87
	global_store_dwordx4 v70, v[24:27], s[10:11]
	v_add_u32_e32 v129, 0xe000, v22
	global_load_dwordx4 v[132:135], v129, s[10:11]
	global_load_dwordx4 v[136:139], v129, s[4:5]
	global_load_dwordx4 v[140:143], v129, s[12:13]
	s_waitcnt vmcnt(8)
; DI unsigned cvtpk(float lo, float hi) { unsigned r; asm volatile("v_cvt_pk_bf16_f32 %0, %1, %2" : "=v"(r) : "v"(lo), "v"(hi)); return r; }
; DI float bflo(unsigned w) { return __uint_as_float(w << 16); }
; DI float bfhi(unsigned w) { return __uint_as_float(w & 0xffff0000u); }
; DI float sigm(float x) { return rcpf_(1.f + ex2(-x * LOG2E)); }
; DI float ub(unsigned w, int i) { return (float)((w >> (8 * i)) & 0xffu); }
; DI void phase_fixup(const Params& p) {
;     ...
;         for (int i = 0; i < 16; ++i) {
;             const size_t off = (size_t)(c * 128 + rq * 32 + 2 * i + r2) * 2048 + ch;
;             const u32x4 g = __builtin_nontemporal_load((const u32x4*)(ZG + off)), h = __builtin_nontemporal_load((const u32x4*)(HLp + off)), pp = __builtin_nontemporal_load((const u32x4*)(PPp + off));
;             u32x4 o;
; #pragma unroll
;             for (int k = 0; k < 4; ++k) {
;                 const float g0 = bflo(g[k]), g1 = bfhi(g[k]);
;                 const float y0 = (bflo(h[k]) + ub(pp[k], 0) * cf[2 * k] + ub(pp[k], 1) * cb[2 * k]) * g0 * sigm(g0);
;                 const float y1 = (bfhi(h[k]) + ub(pp[k], 2) * cf[2 * k + 1] + ub(pp[k], 3) * cb[2 * k + 1]) * g1 * sigm(g1);
;                 o[k] = cvtpk(y0, y1);
;             }
;             *(u32x4*)(ZG + off) = o;
;         }
	v_lshlrev_b32_e32 v72, 16, v54
	v_and_b32_e32 v73, 0xffff0000, v54
	v_lshlrev_b32_e32 v80, 16, v58
	v_and_b32_e32 v81, 0xffff0000, v58
	v_cvt_f32_ubyte0_e32 v88, v62
	v_cvt_f32_ubyte2_e32 v89, v62
	v_cvt_f32_ubyte1_e32 v96, v62
	v_cvt_f32_ubyte3_e32 v97, v62
	v_lshlrev_b32_e32 v74, 16, v55
	v_and_b32_e32 v75, 0xffff0000, v55
	v_lshlrev_b32_e32 v82, 16, v59
	v_and_b32_e32 v83, 0xffff0000, v59
	v_cvt_f32_ubyte0_e32 v90, v63
	v_cvt_f32_ubyte2_e32 v91, v63
	v_cvt_f32_ubyte1_e32 v98, v63
	v_cvt_f32_ubyte3_e32 v99, v63
	v_lshlrev_b32_e32 v76, 16, v56
	v_and_b32_e32 v77, 0xffff0000, v56
	v_lshlrev_b32_e32 v84, 16, v60
	v_and_b32_e32 v85, 0xffff0000, v60
	v_cvt_f32_ubyte0_e32 v92, v64
	v_cvt_f32_ubyte2_e32 v93, v64
	v_cvt_f32_ubyte1_e32 v100, v64
	v_cvt_f32_ubyte3_e32 v101, v64
	v_lshlrev_b32_e32 v78, 16, v57
	v_and_b32_e32 v79, 0xffff0000, v57
	v_lshlrev_b32_e32 v86, 16, v61
	v_and_b32_e32 v87, 0xffff0000, v61
	v_cvt_f32_ubyte0_e32 v94, v65
	v_cvt_f32_ubyte2_e32 v95, v65
	v_cvt_f32_ubyte1_e32 v102, v65
	v_cvt_f32_ubyte3_e32 v103, v65
	v_pk_mul_f32 v[104:105], v[72:73], s[40:41] op_sel_hi:[1,0]
	v_pk_mul_f32 v[106:107], v[74:75], s[40:41] op_sel_hi:[1,0]
	v_pk_mul_f32 v[108:109], v[76:77], s[40:41] op_sel_hi:[1,0]
	v_pk_mul_f32 v[110:111], v[78:79], s[40:41] op_sel_hi:[1,0]
	v_pk_fma_f32 v[80:81], v[88:89], v[18:19], v[80:81]
	v_pk_fma_f32 v[82:83], v[90:91], v[20:21], v[82:83]
	v_pk_fma_f32 v[84:85], v[92:93], v[14:15], v[84:85]
	v_pk_fma_f32 v[86:87], v[94:95], v[16:17], v[86:87]
	v_exp_f32_e32 v104, v104
	v_exp_f32_e32 v105, v105
	v_exp_f32_e32 v106, v106
	v_exp_f32_e32 v107, v107
	v_exp_f32_e32 v108, v108
	v_exp_f32_e32 v109, v109
	v_exp_f32_e32 v110, v110
	v_exp_f32_e32 v111, v111
	v_pk_fma_f32 v[80:81], v[96:97], v[2:3], v[80:81]
	v_pk_fma_f32 v[82:83], v[98:99], v[4:5], v[82:83]
	v_pk_fma_f32 v[84:85], v[100:101], v[6:7], v[84:85]
	v_pk_fma_f32 v[86:87], v[102:103], v[8:9], v[86:87]
	v_pk_add_f32 v[104:105], v[104:105], 1.0 op_sel_hi:[1,0]
	v_pk_add_f32 v[106:107], v[106:107], 1.0 op_sel_hi:[1,0]
	v_pk_add_f32 v[108:109], v[108:109], 1.0 op_sel_hi:[1,0]
	v_pk_add_f32 v[110:111], v[110:111], 1.0 op_sel_hi:[1,0]
	v_rcp_f32_e32 v104, v104
	v_rcp_f32_e32 v105, v105
	v_rcp_f32_e32 v106, v106
	v_rcp_f32_e32 v107, v107
	v_rcp_f32_e32 v108, v108
	v_rcp_f32_e32 v109, v109
	v_rcp_f32_e32 v110, v110
	v_rcp_f32_e32 v111, v111
	v_pk_mul_f32 v[80:81], v[80:81], v[72:73]
	v_pk_mul_f32 v[82:83], v[82:83], v[74:75]
	v_pk_mul_f32 v[84:85], v[84:85], v[76:77]
	v_pk_mul_f32 v[86:87], v[86:87], v[78:79]
	v_pk_mul_f32 v[80:81], v[104:105], v[80:81]
	v_pk_mul_f32 v[82:83], v[106:107], v[82:83]
	v_pk_mul_f32 v[84:85], v[108:109], v[84:85]
	v_pk_mul_f32 v[86:87], v[110:111], v[86:87]
	v_cvt_pk_bf16_f32 v66, v80, v81
	v_cvt_pk_bf16_f32 v67, v82, v83
	v_cvt_pk_bf16_f32 v68, v84, v85
	v_cvt_pk_bf16_f32 v69, v86, v87
	global_store_dwordx4 v71, v[66:69], s[10:11]
	v_add_u32_e32 v70, 0x10000, v22
	global_load_dwordx4 v[28:31], v70, s[10:11]
	global_load_dwordx4 v[32:35], v70, s[4:5]
	global_load_dwordx4 v[36:39], v70, s[12:13]
	s_waitcnt vmcnt(8)
	v_lshlrev_b32_e32 v72, 16, v112
	v_and_b32_e32 v73, 0xffff0000, v112
	v_lshlrev_b32_e32 v80, 16, v116
	v_and_b32_e32 v81, 0xffff0000, v116
	v_cvt_f32_ubyte0_e32 v88, v120
	v_cvt_f32_ubyte2_e32 v89, v120
	v_cvt_f32_ubyte1_e32 v96, v120
	v_cvt_f32_ubyte3_e32 v97, v120
	v_lshlrev_b32_e32 v74, 16, v113
	v_and_b32_e32 v75, 0xffff0000, v113
	v_lshlrev_b32_e32 v82, 16, v117
	v_and_b32_e32 v83, 0xffff0000, v117
	v_cvt_f32_ubyte0_e32 v90, v121
	v_cvt_f32_ubyte2_e32 v91, v121
	v_cvt_f32_ubyte1_e32 v98, v121
	v_cvt_f32_ubyte3_e32 v99, v121
	v_lshlrev_b32_e32 v76, 16, v114
	v_and_b32_e32 v77, 0xffff0000, v114
	v_lshlrev_b32_e32 v84, 16, v118
	v_and_b32_e32 v85, 0xffff0000, v118
	v_cvt_f32_ubyte0_e32 v92, v122
	v_cvt_f32_ubyte2_e32 v93, v122
	v_cvt_f32_ubyte1_e32 v100, v122
	v_cvt_f32_ubyte3_e32 v101, v122
	v_lshlrev_b32_e32 v78, 16, v115
	v_and_b32_e32 v79, 0xffff0000, v115
	v_lshlrev_b32_e32 v86, 16, v119
	v_and_b32_e32 v87, 0xffff0000, v119
	v_cvt_f32_ubyte0_e32 v94, v123
	v_cvt_f32_ubyte2_e32 v95, v123
	v_cvt_f32_ubyte1_e32 v102, v123
	v_cvt_f32_ubyte3_e32 v103, v123
	v_pk_mul_f32 v[104:105], v[72:73], s[40:41] op_sel_hi:[1,0]
	v_pk_mul_f32 v[106:107], v[74:75], s[40:41] op_sel_hi:[1,0]
	v_pk_mul_f32 v[108:109], v[76:77], s[40:41] op_sel_hi:[1,0]
	v_pk_mul_f32 v[110:111], v[78:79], s[40:41] op_sel_hi:[1,0]
	v_pk_fma_f32 v[80:81], v[88:89], v[18:19], v[80:81]
	v_pk_fma_f32 v[82:83], v[90:91], v[20:21], v[82:83]
	v_pk_fma_f32 v[84:85], v[92:93], v[14:15], v[84:85]
	v_pk_fma_f32 v[86:87], v[94:95], v[16:17], v[86:87]
	v_exp_f32_e32 v104, v104
	v_exp_f32_e32 v105, v105
	v_exp_f32_e32 v106, v106
	v_exp_f32_e32 v107, v107
	v_exp_f32_e32 v108, v108
	v_exp_f32_e32 v109, v109
	v_exp_f32_e32 v110, v110
	v_exp_f32_e32 v111, v111
	v_pk_fma_f32 v[80:81], v[96:97], v[2:3], v[80:81]
	v_pk_fma_f32 v[82:83], v[98:99], v[4:5], v[82:83]
	v_pk_fma_f32 v[84:85], v[100:101], v[6:7], v[84:85]
	v_pk_fma_f32 v[86:87], v[102:103], v[8:9], v[86:87]
	v_pk_add_f32 v[104:105], v[104:105], 1.0 op_sel_hi:[1,0]
	v_pk_add_f32 v[106:107], v[106:107], 1.0 op_sel_hi:[1,0]
	v_pk_add_f32 v[108:109], v[108:109], 1.0 op_sel_hi:[1,0]
	v_pk_add_f32 v[110:111], v[110:111], 1.0 op_sel_hi:[1,0]
	v_rcp_f32_e32 v104, v104
	v_rcp_f32_e32 v105, v105
	v_rcp_f32_e32 v106, v106
	v_rcp_f32_e32 v107, v107
	v_rcp_f32_e32 v108, v108
	v_rcp_f32_e32 v109, v109
	v_rcp_f32_e32 v110, v110
	v_rcp_f32_e32 v111, v111
	v_pk_mul_f32 v[80:81], v[80:81], v[72:73]
	v_pk_mul_f32 v[82:83], v[82:83], v[74:75]
	v_pk_mul_f32 v[84:85], v[84:85], v[76:77]
	v_pk_mul_f32 v[86:87], v[86:87], v[78:79]
	v_pk_mul_f32 v[80:81], v[104:105], v[80:81]
	v_pk_mul_f32 v[82:83], v[106:107], v[82:83]
	v_pk_mul_f32 v[84:85], v[108:109], v[84:85]
	v_pk_mul_f32 v[86:87], v[110:111], v[86:87]
	v_cvt_pk_bf16_f32 v124, v80, v81
	v_cvt_pk_bf16_f32 v125, v82, v83
	v_cvt_pk_bf16_f32 v126, v84, v85
	v_cvt_pk_bf16_f32 v127, v86, v87
	global_store_dwordx4 v128, v[124:127], s[10:11]
	v_add_u32_e32 v71, 0x12000, v22
	global_load_dwordx4 v[54:57], v71, s[10:11]
	global_load_dwordx4 v[58:61], v71, s[4:5]
	global_load_dwordx4 v[62:65], v71, s[12:13]
	s_waitcnt vmcnt(8)
; DI unsigned cvtpk(float lo, float hi) { unsigned r; asm volatile("v_cvt_pk_bf16_f32 %0, %1, %2" : "=v"(r) : "v"(lo), "v"(hi)); return r; }
; DI float bflo(unsigned w) { return __uint_as_float(w << 16); }
; DI float bfhi(unsigned w) { return __uint_as_float(w & 0xffff0000u); }
; DI float sigm(float x) { return rcpf_(1.f + ex2(-x * LOG2E)); }
; DI float ub(unsigned w, int i) { return (float)((w >> (8 * i)) & 0xffu); }
; DI void phase_fixup(const Params& p) {
;     ...
;         for (int i = 0; i < 16; ++i) {
;             const size_t off = (size_t)(c * 128 + rq * 32 + 2 * i + r2) * 2048 + ch;
;             const u32x4 g = __builtin_nontemporal_load((const u32x4*)(ZG + off)), h = __builtin_nontemporal_load((const u32x4*)(HLp + off)), pp = __builtin_nontemporal_load((const u32x4*)(PPp + off));
;             u32x4 o;
; #pragma unroll
;             for (int k = 0; k < 4; ++k) {
;                 const float g0 = bflo(g[k]), g1 = bfhi(g[k]);
;                 const float y0 = (bflo(h[k]) + ub(pp[k], 0) * cf[2 * k] + ub(pp[k], 1) * cb[2 * k]) * g0 * sigm(g0);
;                 const float y1 = (bfhi(h[k]) + ub(pp[k], 2) * cf[2 * k + 1] + ub(pp[k], 3) * cb[2 * k + 1]) * g1 * sigm(g1);
;                 o[k] = cvtpk(y0, y1);
;             }
;             *(u32x4*)(ZG + off) = o;
;         }
	v_lshlrev_b32_e32 v72, 16, v132
	v_and_b32_e32 v73, 0xffff0000, v132
	v_lshlrev_b32_e32 v80, 16, v136
	v_and_b32_e32 v81, 0xffff0000, v136
	v_cvt_f32_ubyte0_e32 v88, v140
	v_cvt_f32_ubyte2_e32 v89, v140
	v_cvt_f32_ubyte1_e32 v96, v140
	v_cvt_f32_ubyte3_e32 v97, v140
	v_lshlrev_b32_e32 v74, 16, v133
	v_and_b32_e32 v75, 0xffff0000, v133
	v_lshlrev_b32_e32 v82, 16, v137
	v_and_b32_e32 v83, 0xffff0000, v137
	v_cvt_f32_ubyte0_e32 v90, v141
	v_cvt_f32_ubyte2_e32 v91, v141
	v_cvt_f32_ubyte1_e32 v98, v141
	v_cvt_f32_ubyte3_e32 v99, v141
	v_lshlrev_b32_e32 v76, 16, v134
	v_and_b32_e32 v77, 0xffff0000, v134
	v_lshlrev_b32_e32 v84, 16, v138
	v_and_b32_e32 v85, 0xffff0000, v138
	v_cvt_f32_ubyte0_e32 v92, v142
	v_cvt_f32_ubyte2_e32 v93, v142
	v_cvt_f32_ubyte1_e32 v100, v142
	v_cvt_f32_ubyte3_e32 v101, v142
	v_lshlrev_b32_e32 v78, 16, v135
	v_and_b32_e32 v79, 0xffff0000, v135
	v_lshlrev_b32_e32 v86, 16, v139
	v_and_b32_e32 v87, 0xffff0000, v139
	v_cvt_f32_ubyte0_e32 v94, v143
	v_cvt_f32_ubyte2_e32 v95, v143
	v_cvt_f32_ubyte1_e32 v102, v143
	v_cvt_f32_ubyte3_e32 v103, v143
	v_pk_mul_f32 v[104:105], v[72:73], s[40:41] op_sel_hi:[1,0]
	v_pk_mul_f32 v[106:107], v[74:75], s[40:41] op_sel_hi:[1,0]
	v_pk_mul_f32 v[108:109], v[76:77], s[40:41] op_sel_hi:[1,0]
	v_pk_mul_f32 v[110:111], v[78:79], s[40:41] op_sel_hi:[1,0]
	v_pk_fma_f32 v[80:81], v[88:89], v[18:19], v[80:81]
	v_pk_fma_f32 v[82:83], v[90:91], v[20:21], v[82:83]
	v_pk_fma_f32 v[84:85], v[92:93], v[14:15], v[84:85]
	v_pk_fma_f32 v[86:87], v[94:95], v[16:17], v[86:87]
	v_exp_f32_e32 v104, v104
	v_exp_f32_e32 v105, v105
	v_exp_f32_e32 v106, v106
	v_exp_f32_e32 v107, v107
	v_exp_f32_e32 v108, v108
	v_exp_f32_e32 v109, v109
	v_exp_f32_e32 v110, v110
	v_exp_f32_e32 v111, v111
	v_pk_fma_f32 v[80:81], v[96:97], v[2:3], v[80:81]
	v_pk_fma_f32 v[82:83], v[98:99], v[4:5], v[82:83]
	v_pk_fma_f32 v[84:85], v[100:101], v[6:7], v[84:85]
	v_pk_fma_f32 v[86:87], v[102:103], v[8:9], v[86:87]
	v_pk_add_f32 v[104:105], v[104:105], 1.0 op_sel_hi:[1,0]
	v_pk_add_f32 v[106:107], v[106:107], 1.0 op_sel_hi:[1,0]
	v_pk_add_f32 v[108:109], v[108:109], 1.0 op_sel_hi:[1,0]
	v_pk_add_f32 v[110:111], v[110:111], 1.0 op_sel_hi:[1,0]
	v_rcp_f32_e32 v104, v104
	v_rcp_f32_e32 v105, v105
	v_rcp_f32_e32 v106, v106
	v_rcp_f32_e32 v107, v107
	v_rcp_f32_e32 v108, v108
	v_rcp_f32_e32 v109, v109
	v_rcp_f32_e32 v110, v110
	v_rcp_f32_e32 v111, v111
	v_pk_mul_f32 v[80:81], v[80:81], v[72:73]
	v_pk_mul_f32 v[82:83], v[82:83], v[74:75]
	v_pk_mul_f32 v[84:85], v[84:85], v[76:77]
	v_pk_mul_f32 v[86:87], v[86:87], v[78:79]
	v_pk_mul_f32 v[80:81], v[104:105], v[80:81]
	v_pk_mul_f32 v[82:83], v[106:107], v[82:83]
	v_pk_mul_f32 v[84:85], v[108:109], v[84:85]
	v_pk_mul_f32 v[86:87], v[110:111], v[86:87]
	v_cvt_pk_bf16_f32 v144, v80, v81
	v_cvt_pk_bf16_f32 v145, v82, v83
	v_cvt_pk_bf16_f32 v146, v84, v85
	v_cvt_pk_bf16_f32 v147, v86, v87
	global_store_dwordx4 v129, v[144:147], s[10:11]
	v_add_u32_e32 v128, 0x14000, v22
	global_load_dwordx4 v[112:115], v128, s[10:11]
	global_load_dwordx4 v[116:119], v128, s[4:5]
	global_load_dwordx4 v[120:123], v128, s[12:13]
	s_waitcnt vmcnt(8)
	v_lshlrev_b32_e32 v72, 16, v28
	v_and_b32_e32 v73, 0xffff0000, v28
	v_lshlrev_b32_e32 v80, 16, v32
	v_and_b32_e32 v81, 0xffff0000, v32
	v_cvt_f32_ubyte0_e32 v88, v36
	v_cvt_f32_ubyte2_e32 v89, v36
	v_cvt_f32_ubyte1_e32 v96, v36
	v_cvt_f32_ubyte3_e32 v97, v36
	v_lshlrev_b32_e32 v74, 16, v29
	v_and_b32_e32 v75, 0xffff0000, v29
	v_lshlrev_b32_e32 v82, 16, v33
	v_and_b32_e32 v83, 0xffff0000, v33
	v_cvt_f32_ubyte0_e32 v90, v37
	v_cvt_f32_ubyte2_e32 v91, v37
	v_cvt_f32_ubyte1_e32 v98, v37
	v_cvt_f32_ubyte3_e32 v99, v37
	v_lshlrev_b32_e32 v76, 16, v30
	v_and_b32_e32 v77, 0xffff0000, v30
	v_lshlrev_b32_e32 v84, 16, v34
	v_and_b32_e32 v85, 0xffff0000, v34
	v_cvt_f32_ubyte0_e32 v92, v38
	v_cvt_f32_ubyte2_e32 v93, v38
	v_cvt_f32_ubyte1_e32 v100, v38
	v_cvt_f32_ubyte3_e32 v101, v38
	v_lshlrev_b32_e32 v78, 16, v31
	v_and_b32_e32 v79, 0xffff0000, v31
	v_lshlrev_b32_e32 v86, 16, v35
	v_and_b32_e32 v87, 0xffff0000, v35
	v_cvt_f32_ubyte0_e32 v94, v39
	v_cvt_f32_ubyte2_e32 v95, v39
	v_cvt_f32_ubyte1_e32 v102, v39
	v_cvt_f32_ubyte3_e32 v103, v39
	v_pk_mul_f32 v[104:105], v[72:73], s[40:41] op_sel_hi:[1,0]
	v_pk_mul_f32 v[106:107], v[74:75], s[40:41] op_sel_hi:[1,0]
	v_pk_mul_f32 v[108:109], v[76:77], s[40:41] op_sel_hi:[1,0]
	v_pk_mul_f32 v[110:111], v[78:79], s[40:41] op_sel_hi:[1,0]
	v_pk_fma_f32 v[80:81], v[88:89], v[18:19], v[80:81]
	v_pk_fma_f32 v[82:83], v[90:91], v[20:21], v[82:83]
	v_pk_fma_f32 v[84:85], v[92:93], v[14:15], v[84:85]
	v_pk_fma_f32 v[86:87], v[94:95], v[16:17], v[86:87]
	v_exp_f32_e32 v104, v104
	v_exp_f32_e32 v105, v105
	v_exp_f32_e32 v106, v106
	v_exp_f32_e32 v107, v107
	v_exp_f32_e32 v108, v108
	v_exp_f32_e32 v109, v109
	v_exp_f32_e32 v110, v110
	v_exp_f32_e32 v111, v111
	v_pk_fma_f32 v[80:81], v[96:97], v[2:3], v[80:81]
	v_pk_fma_f32 v[82:83], v[98:99], v[4:5], v[82:83]
	v_pk_fma_f32 v[84:85], v[100:101], v[6:7], v[84:85]
	v_pk_fma_f32 v[86:87], v[102:103], v[8:9], v[86:87]
	v_pk_add_f32 v[104:105], v[104:105], 1.0 op_sel_hi:[1,0]
	v_pk_add_f32 v[106:107], v[106:107], 1.0 op_sel_hi:[1,0]
	v_pk_add_f32 v[108:109], v[108:109], 1.0 op_sel_hi:[1,0]
	v_pk_add_f32 v[110:111], v[110:111], 1.0 op_sel_hi:[1,0]
	v_rcp_f32_e32 v104, v104
	v_rcp_f32_e32 v105, v105
	v_rcp_f32_e32 v106, v106
	v_rcp_f32_e32 v107, v107
	v_rcp_f32_e32 v108, v108
	v_rcp_f32_e32 v109, v109
	v_rcp_f32_e32 v110, v110
	v_rcp_f32_e32 v111, v111
	v_pk_mul_f32 v[80:81], v[80:81], v[72:73]
	v_pk_mul_f32 v[82:83], v[82:83], v[74:75]
	v_pk_mul_f32 v[84:85], v[84:85], v[76:77]
	v_pk_mul_f32 v[86:87], v[86:87], v[78:79]
	v_pk_mul_f32 v[80:81], v[104:105], v[80:81]
	v_pk_mul_f32 v[82:83], v[106:107], v[82:83]
	v_pk_mul_f32 v[84:85], v[108:109], v[84:85]
	v_pk_mul_f32 v[86:87], v[110:111], v[86:87]
	v_cvt_pk_bf16_f32 v24, v80, v81
	v_cvt_pk_bf16_f32 v25, v82, v83
	v_cvt_pk_bf16_f32 v26, v84, v85
	v_cvt_pk_bf16_f32 v27, v86, v87
	global_store_dwordx4 v70, v[24:27], s[10:11]
	v_add_u32_e32 v129, 0x16000, v22
	global_load_dwordx4 v[132:135], v129, s[10:11]
	global_load_dwordx4 v[136:139], v129, s[4:5]
	global_load_dwordx4 v[140:143], v129, s[12:13]
	s_waitcnt vmcnt(8)
; DI unsigned cvtpk(float lo, float hi) { unsigned r; asm volatile("v_cvt_pk_bf16_f32 %0, %1, %2" : "=v"(r) : "v"(lo), "v"(hi)); return r; }
; DI float bflo(unsigned w) { return __uint_as_float(w << 16); }
; DI float bfhi(unsigned w) { return __uint_as_float(w & 0xffff0000u); }
; DI float sigm(float x) { return rcpf_(1.f + ex2(-x * LOG2E)); }
; DI float ub(unsigned w, int i) { return (float)((w >> (8 * i)) & 0xffu); }
; DI void phase_fixup(const Params& p) {
;     ...
;         for (int i = 0; i < 16; ++i) {
;             const size_t off = (size_t)(c * 128 + rq * 32 + 2 * i + r2) * 2048 + ch;
;             const u32x4 g = __builtin_nontemporal_load((const u32x4*)(ZG + off)), h = __builtin_nontemporal_load((const u32x4*)(HLp + off)), pp = __builtin_nontemporal_load((const u32x4*)(PPp + off));
;             u32x4 o;
; #pragma unroll
;             for (int k = 0; k < 4; ++k) {
;                 const float g0 = bflo(g[k]), g1 = bfhi(g[k]);
;                 const float y0 = (bflo(h[k]) + ub(pp[k], 0) * cf[2 * k] + ub(pp[k], 1) * cb[2 * k]) * g0 * sigm(g0);
;                 const float y1 = (bfhi(h[k]) + ub(pp[k], 2) * cf[2 * k + 1] + ub(pp[k], 3) * cb[2 * k + 1]) * g1 * sigm(g1);
;                 o[k] = cvtpk(y0, y1);
;             }
;             *(u32x4*)(ZG + off) = o;
;         }
	v_lshlrev_b32_e32 v72, 16, v54
	v_and_b32_e32 v73, 0xffff0000, v54
	v_lshlrev_b32_e32 v80, 16, v58
	v_and_b32_e32 v81, 0xffff0000, v58
	v_cvt_f32_ubyte0_e32 v88, v62
	v_cvt_f32_ubyte2_e32 v89, v62
	v_cvt_f32_ubyte1_e32 v96, v62
	v_cvt_f32_ubyte3_e32 v97, v62
	v_lshlrev_b32_e32 v74, 16, v55
	v_and_b32_e32 v75, 0xffff0000, v55
	v_lshlrev_b32_e32 v82, 16, v59
	v_and_b32_e32 v83, 0xffff0000, v59
	v_cvt_f32_ubyte0_e32 v90, v63
	v_cvt_f32_ubyte2_e32 v91, v63
	v_cvt_f32_ubyte1_e32 v98, v63
	v_cvt_f32_ubyte3_e32 v99, v63
	v_lshlrev_b32_e32 v76, 16, v56
	v_and_b32_e32 v77, 0xffff0000, v56
	v_lshlrev_b32_e32 v84, 16, v60
	v_and_b32_e32 v85, 0xffff0000, v60
	v_cvt_f32_ubyte0_e32 v92, v64
	v_cvt_f32_ubyte2_e32 v93, v64
	v_cvt_f32_ubyte1_e32 v100, v64
	v_cvt_f32_ubyte3_e32 v101, v64
	v_lshlrev_b32_e32 v78, 16, v57
	v_and_b32_e32 v79, 0xffff0000, v57
	v_lshlrev_b32_e32 v86, 16, v61
	v_and_b32_e32 v87, 0xffff0000, v61
	v_cvt_f32_ubyte0_e32 v94, v65
	v_cvt_f32_ubyte2_e32 v95, v65
	v_cvt_f32_ubyte1_e32 v102, v65
	v_cvt_f32_ubyte3_e32 v103, v65
	v_pk_mul_f32 v[104:105], v[72:73], s[40:41] op_sel_hi:[1,0]
	v_pk_mul_f32 v[106:107], v[74:75], s[40:41] op_sel_hi:[1,0]
	v_pk_mul_f32 v[108:109], v[76:77], s[40:41] op_sel_hi:[1,0]
	v_pk_mul_f32 v[110:111], v[78:79], s[40:41] op_sel_hi:[1,0]
	v_pk_fma_f32 v[80:81], v[88:89], v[18:19], v[80:81]
	v_pk_fma_f32 v[82:83], v[90:91], v[20:21], v[82:83]
	v_pk_fma_f32 v[84:85], v[92:93], v[14:15], v[84:85]
	v_pk_fma_f32 v[86:87], v[94:95], v[16:17], v[86:87]
	v_exp_f32_e32 v104, v104
	v_exp_f32_e32 v105, v105
	v_exp_f32_e32 v106, v106
	v_exp_f32_e32 v107, v107
	v_exp_f32_e32 v108, v108
	v_exp_f32_e32 v109, v109
	v_exp_f32_e32 v110, v110
	v_exp_f32_e32 v111, v111
	v_pk_fma_f32 v[80:81], v[96:97], v[2:3], v[80:81]
	v_pk_fma_f32 v[82:83], v[98:99], v[4:5], v[82:83]
	v_pk_fma_f32 v[84:85], v[100:101], v[6:7], v[84:85]
	v_pk_fma_f32 v[86:87], v[102:103], v[8:9], v[86:87]
	v_pk_add_f32 v[104:105], v[104:105], 1.0 op_sel_hi:[1,0]
	v_pk_add_f32 v[106:107], v[106:107], 1.0 op_sel_hi:[1,0]
	v_pk_add_f32 v[108:109], v[108:109], 1.0 op_sel_hi:[1,0]
	v_pk_add_f32 v[110:111], v[110:111], 1.0 op_sel_hi:[1,0]
	v_rcp_f32_e32 v104, v104
	v_rcp_f32_e32 v105, v105
	v_rcp_f32_e32 v106, v106
	v_rcp_f32_e32 v107, v107
	v_rcp_f32_e32 v108, v108
	v_rcp_f32_e32 v109, v109
	v_rcp_f32_e32 v110, v110
	v_rcp_f32_e32 v111, v111
	v_pk_mul_f32 v[80:81], v[80:81], v[72:73]
	v_pk_mul_f32 v[82:83], v[82:83], v[74:75]
	v_pk_mul_f32 v[84:85], v[84:85], v[76:77]
	v_pk_mul_f32 v[86:87], v[86:87], v[78:79]
	v_pk_mul_f32 v[80:81], v[104:105], v[80:81]
	v_pk_mul_f32 v[82:83], v[106:107], v[82:83]
	v_pk_mul_f32 v[84:85], v[108:109], v[84:85]
	v_pk_mul_f32 v[86:87], v[110:111], v[86:87]
	v_cvt_pk_bf16_f32 v66, v80, v81
	v_cvt_pk_bf16_f32 v67, v82, v83
	v_cvt_pk_bf16_f32 v68, v84, v85
	v_cvt_pk_bf16_f32 v69, v86, v87
	global_store_dwordx4 v71, v[66:69], s[10:11]
	v_add_u32_e32 v70, 0x18000, v22
	global_load_dwordx4 v[28:31], v70, s[10:11]
	global_load_dwordx4 v[32:35], v70, s[4:5]
	global_load_dwordx4 v[36:39], v70, s[12:13]
	s_waitcnt vmcnt(8)
	v_lshlrev_b32_e32 v72, 16, v112
	v_and_b32_e32 v73, 0xffff0000, v112
	v_lshlrev_b32_e32 v80, 16, v116
	v_and_b32_e32 v81, 0xffff0000, v116
	v_cvt_f32_ubyte0_e32 v88, v120
	v_cvt_f32_ubyte2_e32 v89, v120
	v_cvt_f32_ubyte1_e32 v96, v120
	v_cvt_f32_ubyte3_e32 v97, v120
	v_lshlrev_b32_e32 v74, 16, v113
	v_and_b32_e32 v75, 0xffff0000, v113
	v_lshlrev_b32_e32 v82, 16, v117
	v_and_b32_e32 v83, 0xffff0000, v117
	v_cvt_f32_ubyte0_e32 v90, v121
	v_cvt_f32_ubyte2_e32 v91, v121
	v_cvt_f32_ubyte1_e32 v98, v121
	v_cvt_f32_ubyte3_e32 v99, v121
	v_lshlrev_b32_e32 v76, 16, v114
	v_and_b32_e32 v77, 0xffff0000, v114
	v_lshlrev_b32_e32 v84, 16, v118
	v_and_b32_e32 v85, 0xffff0000, v118
	v_cvt_f32_ubyte0_e32 v92, v122
	v_cvt_f32_ubyte2_e32 v93, v122
	v_cvt_f32_ubyte1_e32 v100, v122
	v_cvt_f32_ubyte3_e32 v101, v122
	v_lshlrev_b32_e32 v78, 16, v115
	v_and_b32_e32 v79, 0xffff0000, v115
	v_lshlrev_b32_e32 v86, 16, v119
	v_and_b32_e32 v87, 0xffff0000, v119
	v_cvt_f32_ubyte0_e32 v94, v123
	v_cvt_f32_ubyte2_e32 v95, v123
	v_cvt_f32_ubyte1_e32 v102, v123
	v_cvt_f32_ubyte3_e32 v103, v123
	v_pk_mul_f32 v[104:105], v[72:73], s[40:41] op_sel_hi:[1,0]
	v_pk_mul_f32 v[106:107], v[74:75], s[40:41] op_sel_hi:[1,0]
	v_pk_mul_f32 v[108:109], v[76:77], s[40:41] op_sel_hi:[1,0]
	v_pk_mul_f32 v[110:111], v[78:79], s[40:41] op_sel_hi:[1,0]
	v_pk_fma_f32 v[80:81], v[88:89], v[18:19], v[80:81]
	v_pk_fma_f32 v[82:83], v[90:91], v[20:21], v[82:83]
	v_pk_fma_f32 v[84:85], v[92:93], v[14:15], v[84:85]
	v_pk_fma_f32 v[86:87], v[94:95], v[16:17], v[86:87]
	v_exp_f32_e32 v104, v104
	v_exp_f32_e32 v105, v105
	v_exp_f32_e32 v106, v106
	v_exp_f32_e32 v107, v107
	v_exp_f32_e32 v108, v108
	v_exp_f32_e32 v109, v109
	v_exp_f32_e32 v110, v110
	v_exp_f32_e32 v111, v111
	v_pk_fma_f32 v[80:81], v[96:97], v[2:3], v[80:81]
	v_pk_fma_f32 v[82:83], v[98:99], v[4:5], v[82:83]
	v_pk_fma_f32 v[84:85], v[100:101], v[6:7], v[84:85]
	v_pk_fma_f32 v[86:87], v[102:103], v[8:9], v[86:87]
	v_pk_add_f32 v[104:105], v[104:105], 1.0 op_sel_hi:[1,0]
	v_pk_add_f32 v[106:107], v[106:107], 1.0 op_sel_hi:[1,0]
	v_pk_add_f32 v[108:109], v[108:109], 1.0 op_sel_hi:[1,0]
	v_pk_add_f32 v[110:111], v[110:111], 1.0 op_sel_hi:[1,0]
	v_rcp_f32_e32 v104, v104
	v_rcp_f32_e32 v105, v105
	v_rcp_f32_e32 v106, v106
	v_rcp_f32_e32 v107, v107
	v_rcp_f32_e32 v108, v108
	v_rcp_f32_e32 v109, v109
	v_rcp_f32_e32 v110, v110
	v_rcp_f32_e32 v111, v111
	v_pk_mul_f32 v[80:81], v[80:81], v[72:73]
	v_pk_mul_f32 v[82:83], v[82:83], v[74:75]
	v_pk_mul_f32 v[84:85], v[84:85], v[76:77]
	v_pk_mul_f32 v[86:87], v[86:87], v[78:79]
	v_pk_mul_f32 v[80:81], v[104:105], v[80:81]
	v_pk_mul_f32 v[82:83], v[106:107], v[82:83]
	v_pk_mul_f32 v[84:85], v[108:109], v[84:85]
	v_pk_mul_f32 v[86:87], v[110:111], v[86:87]
	v_cvt_pk_bf16_f32 v124, v80, v81
	v_cvt_pk_bf16_f32 v125, v82, v83
	v_cvt_pk_bf16_f32 v126, v84, v85
	v_cvt_pk_bf16_f32 v127, v86, v87
	global_store_dwordx4 v128, v[124:127], s[10:11]
	v_add_u32_e32 v71, 0x1a000, v22
	global_load_dwordx4 v[54:57], v71, s[10:11]
	global_load_dwordx4 v[58:61], v71, s[4:5]
	global_load_dwordx4 v[62:65], v71, s[12:13]
	s_waitcnt vmcnt(8)
; DI unsigned cvtpk(float lo, float hi) { unsigned r; asm volatile("v_cvt_pk_bf16_f32 %0, %1, %2" : "=v"(r) : "v"(lo), "v"(hi)); return r; }
; DI float bflo(unsigned w) { return __uint_as_float(w << 16); }
; DI float bfhi(unsigned w) { return __uint_as_float(w & 0xffff0000u); }
; DI float sigm(float x) { return rcpf_(1.f + ex2(-x * LOG2E)); }
; DI float ub(unsigned w, int i) { return (float)((w >> (8 * i)) & 0xffu); }
; DI void phase_fixup(const Params& p) {
;     ...
;         for (int i = 0; i < 16; ++i) {
;             const size_t off = (size_t)(c * 128 + rq * 32 + 2 * i + r2) * 2048 + ch;
;             const u32x4 g = __builtin_nontemporal_load((const u32x4*)(ZG + off)), h = __builtin_nontemporal_load((const u32x4*)(HLp + off)), pp = __builtin_nontemporal_load((const u32x4*)(PPp + off));
;             u32x4 o;
; #pragma unroll
;             for (int k = 0; k < 4; ++k) {
;                 const float g0 = bflo(g[k]), g1 = bfhi(g[k]);
;                 const float y0 = (bflo(h[k]) + ub(pp[k], 0) * cf[2 * k] + ub(pp[k], 1) * cb[2 * k]) * g0 * sigm(g0);
;                 const float y1 = (bfhi(h[k]) + ub(pp[k], 2) * cf[2 * k + 1] + ub(pp[k], 3) * cb[2 * k + 1]) * g1 * sigm(g1);
;                 o[k] = cvtpk(y0, y1);
;             }
;             *(u32x4*)(ZG + off) = o;
	v_lshlrev_b32_e32 v72, 16, v132
	v_and_b32_e32 v73, 0xffff0000, v132
	v_lshlrev_b32_e32 v80, 16, v136
	v_and_b32_e32 v81, 0xffff0000, v136
	v_cvt_f32_ubyte0_e32 v88, v140
	v_cvt_f32_ubyte2_e32 v89, v140
	v_cvt_f32_ubyte1_e32 v96, v140
	v_cvt_f32_ubyte3_e32 v97, v140
	v_lshlrev_b32_e32 v74, 16, v133
	v_and_b32_e32 v75, 0xffff0000, v133
	v_lshlrev_b32_e32 v82, 16, v137
	v_and_b32_e32 v83, 0xffff0000, v137
	v_cvt_f32_ubyte0_e32 v90, v141
	v_cvt_f32_ubyte2_e32 v91, v141
	v_cvt_f32_ubyte1_e32 v98, v141
	v_cvt_f32_ubyte3_e32 v99, v141
	v_lshlrev_b32_e32 v76, 16, v134
	v_and_b32_e32 v77, 0xffff0000, v134
	v_lshlrev_b32_e32 v84, 16, v138
	v_and_b32_e32 v85, 0xffff0000, v138
	v_cvt_f32_ubyte0_e32 v92, v142
	v_cvt_f32_ubyte2_e32 v93, v142
	v_cvt_f32_ubyte1_e32 v100, v142
	v_cvt_f32_ubyte3_e32 v101, v142
	v_lshlrev_b32_e32 v78, 16, v135
	v_and_b32_e32 v79, 0xffff0000, v135
	v_lshlrev_b32_e32 v86, 16, v139
	v_and_b32_e32 v87, 0xffff0000, v139
	v_cvt_f32_ubyte0_e32 v94, v143
	v_cvt_f32_ubyte2_e32 v95, v143
	v_cvt_f32_ubyte1_e32 v102, v143
	v_cvt_f32_ubyte3_e32 v103, v143
	v_pk_mul_f32 v[104:105], v[72:73], s[40:41] op_sel_hi:[1,0]
	v_pk_mul_f32 v[106:107], v[74:75], s[40:41] op_sel_hi:[1,0]
	v_pk_mul_f32 v[108:109], v[76:77], s[40:41] op_sel_hi:[1,0]
	v_pk_mul_f32 v[110:111], v[78:79], s[40:41] op_sel_hi:[1,0]
	v_pk_fma_f32 v[80:81], v[88:89], v[18:19], v[80:81]
	v_pk_fma_f32 v[82:83], v[90:91], v[20:21], v[82:83]
	v_pk_fma_f32 v[84:85], v[92:93], v[14:15], v[84:85]
	v_pk_fma_f32 v[86:87], v[94:95], v[16:17], v[86:87]
	v_exp_f32_e32 v104, v104
	v_exp_f32_e32 v105, v105
	v_exp_f32_e32 v106, v106
	v_exp_f32_e32 v107, v107
	v_exp_f32_e32 v108, v108
	v_exp_f32_e32 v109, v109
	v_exp_f32_e32 v110, v110
	v_exp_f32_e32 v111, v111
	v_pk_fma_f32 v[80:81], v[96:97], v[2:3], v[80:81]
	v_pk_fma_f32 v[82:83], v[98:99], v[4:5], v[82:83]
	v_pk_fma_f32 v[84:85], v[100:101], v[6:7], v[84:85]
	v_pk_fma_f32 v[86:87], v[102:103], v[8:9], v[86:87]
	v_pk_add_f32 v[104:105], v[104:105], 1.0 op_sel_hi:[1,0]
	v_pk_add_f32 v[106:107], v[106:107], 1.0 op_sel_hi:[1,0]
	v_pk_add_f32 v[108:109], v[108:109], 1.0 op_sel_hi:[1,0]
	v_pk_add_f32 v[110:111], v[110:111], 1.0 op_sel_hi:[1,0]
	v_rcp_f32_e32 v104, v104
	v_rcp_f32_e32 v105, v105
	v_rcp_f32_e32 v106, v106
	v_rcp_f32_e32 v107, v107
	v_rcp_f32_e32 v108, v108
	v_rcp_f32_e32 v109, v109
	v_rcp_f32_e32 v110, v110
	v_rcp_f32_e32 v111, v111
	v_pk_mul_f32 v[80:81], v[80:81], v[72:73]
	v_pk_mul_f32 v[82:83], v[82:83], v[74:75]
	v_pk_mul_f32 v[84:85], v[84:85], v[76:77]
	v_pk_mul_f32 v[86:87], v[86:87], v[78:79]
	v_pk_mul_f32 v[80:81], v[104:105], v[80:81]
	v_pk_mul_f32 v[82:83], v[106:107], v[82:83]
	v_pk_mul_f32 v[84:85], v[108:109], v[84:85]
	v_pk_mul_f32 v[86:87], v[110:111], v[86:87]
	v_cvt_pk_bf16_f32 v144, v80, v81
	v_cvt_pk_bf16_f32 v145, v82, v83
	v_cvt_pk_bf16_f32 v146, v84, v85
	v_cvt_pk_bf16_f32 v147, v86, v87
	global_store_dwordx4 v129, v[144:147], s[10:11]
	v_add_u32_e32 v128, 0x1c000, v22
	global_load_dwordx4 v[112:115], v128, s[10:11]
	global_load_dwordx4 v[116:119], v128, s[4:5]
	global_load_dwordx4 v[120:123], v128, s[12:13]
	s_waitcnt vmcnt(8)
	v_lshlrev_b32_e32 v72, 16, v28
	v_and_b32_e32 v73, 0xffff0000, v28
	v_lshlrev_b32_e32 v80, 16, v32
	v_and_b32_e32 v81, 0xffff0000, v32
	v_cvt_f32_ubyte0_e32 v88, v36
	v_cvt_f32_ubyte2_e32 v89, v36
	v_cvt_f32_ubyte1_e32 v96, v36
	v_cvt_f32_ubyte3_e32 v97, v36
	v_lshlrev_b32_e32 v74, 16, v29
	v_and_b32_e32 v75, 0xffff0000, v29
	v_lshlrev_b32_e32 v82, 16, v33
	v_and_b32_e32 v83, 0xffff0000, v33
	v_cvt_f32_ubyte0_e32 v90, v37
	v_cvt_f32_ubyte2_e32 v91, v37
	v_cvt_f32_ubyte1_e32 v98, v37
	v_cvt_f32_ubyte3_e32 v99, v37
	v_lshlrev_b32_e32 v76, 16, v30
	v_and_b32_e32 v77, 0xffff0000, v30
	v_lshlrev_b32_e32 v84, 16, v34
	v_and_b32_e32 v85, 0xffff0000, v34
	v_cvt_f32_ubyte0_e32 v92, v38
	v_cvt_f32_ubyte2_e32 v93, v38
	v_cvt_f32_ubyte1_e32 v100, v38
	v_cvt_f32_ubyte3_e32 v101, v38
	v_lshlrev_b32_e32 v78, 16, v31
	v_and_b32_e32 v79, 0xffff0000, v31
	v_lshlrev_b32_e32 v86, 16, v35
	v_and_b32_e32 v87, 0xffff0000, v35
	v_cvt_f32_ubyte0_e32 v94, v39
	v_cvt_f32_ubyte2_e32 v95, v39
	v_cvt_f32_ubyte1_e32 v102, v39
	v_cvt_f32_ubyte3_e32 v103, v39
	v_pk_mul_f32 v[104:105], v[72:73], s[40:41] op_sel_hi:[1,0]
	v_pk_mul_f32 v[106:107], v[74:75], s[40:41] op_sel_hi:[1,0]
	v_pk_mul_f32 v[108:109], v[76:77], s[40:41] op_sel_hi:[1,0]
	v_pk_mul_f32 v[110:111], v[78:79], s[40:41] op_sel_hi:[1,0]
	v_pk_fma_f32 v[80:81], v[88:89], v[18:19], v[80:81]
	v_pk_fma_f32 v[82:83], v[90:91], v[20:21], v[82:83]
	v_pk_fma_f32 v[84:85], v[92:93], v[14:15], v[84:85]
	v_pk_fma_f32 v[86:87], v[94:95], v[16:17], v[86:87]
	v_exp_f32_e32 v104, v104
	v_exp_f32_e32 v105, v105
	v_exp_f32_e32 v106, v106
	v_exp_f32_e32 v107, v107
	v_exp_f32_e32 v108, v108
	v_exp_f32_e32 v109, v109
	v_exp_f32_e32 v110, v110
	v_exp_f32_e32 v111, v111
	v_pk_fma_f32 v[80:81], v[96:97], v[2:3], v[80:81]
	v_pk_fma_f32 v[82:83], v[98:99], v[4:5], v[82:83]
	v_pk_fma_f32 v[84:85], v[100:101], v[6:7], v[84:85]
	v_pk_fma_f32 v[86:87], v[102:103], v[8:9], v[86:87]
	v_pk_add_f32 v[104:105], v[104:105], 1.0 op_sel_hi:[1,0]
	v_pk_add_f32 v[106:107], v[106:107], 1.0 op_sel_hi:[1,0]
	v_pk_add_f32 v[108:109], v[108:109], 1.0 op_sel_hi:[1,0]
	v_pk_add_f32 v[110:111], v[110:111], 1.0 op_sel_hi:[1,0]
	v_rcp_f32_e32 v104, v104
	v_rcp_f32_e32 v105, v105
	v_rcp_f32_e32 v106, v106
	v_rcp_f32_e32 v107, v107
	v_rcp_f32_e32 v108, v108
	v_rcp_f32_e32 v109, v109
	v_rcp_f32_e32 v110, v110
	v_rcp_f32_e32 v111, v111
	v_pk_mul_f32 v[80:81], v[80:81], v[72:73]
	v_pk_mul_f32 v[82:83], v[82:83], v[74:75]
	v_pk_mul_f32 v[84:85], v[84:85], v[76:77]
	v_pk_mul_f32 v[86:87], v[86:87], v[78:79]
	v_pk_mul_f32 v[80:81], v[104:105], v[80:81]
	v_pk_mul_f32 v[82:83], v[106:107], v[82:83]
	v_pk_mul_f32 v[84:85], v[108:109], v[84:85]
	v_pk_mul_f32 v[86:87], v[110:111], v[86:87]
	v_cvt_pk_bf16_f32 v24, v80, v81
	v_cvt_pk_bf16_f32 v25, v82, v83
	v_cvt_pk_bf16_f32 v26, v84, v85
	v_cvt_pk_bf16_f32 v27, v86, v87
	global_store_dwordx4 v70, v[24:27], s[10:11]
	v_add_u32_e32 v129, 0x1e000, v22
	global_load_dwordx4 v[132:135], v129, s[10:11]
	global_load_dwordx4 v[136:139], v129, s[4:5]
	global_load_dwordx4 v[140:143], v129, s[12:13]
	s_waitcnt vmcnt(8)
; DI unsigned cvtpk(float lo, float hi) { unsigned r; asm volatile("v_cvt_pk_bf16_f32 %0, %1, %2" : "=v"(r) : "v"(lo), "v"(hi)); return r; }
; DI float bflo(unsigned w) { return __uint_as_float(w << 16); }
; DI float bfhi(unsigned w) { return __uint_as_float(w & 0xffff0000u); }
; DI float sigm(float x) { return rcpf_(1.f + ex2(-x * LOG2E)); }
; DI float ub(unsigned w, int i) { return (float)((w >> (8 * i)) & 0xffu); }
; DI void phase_fixup(const Params& p) {
;     ...
;         for (int i = 0; i < 16; ++i) {
;             const size_t off = (size_t)(c * 128 + rq * 32 + 2 * i + r2) * 2048 + ch;
;             const u32x4 g = __builtin_nontemporal_load((const u32x4*)(ZG + off)), h = __builtin_nontemporal_load((const u32x4*)(HLp + off)), pp = __builtin_nontemporal_load((const u32x4*)(PPp + off));
;             u32x4 o;
; #pragma unroll
;             for (int k = 0; k < 4; ++k) {
;                 const float g0 = bflo(g[k]), g1 = bfhi(g[k]);
;                 const float y0 = (bflo(h[k]) + ub(pp[k], 0) * cf[2 * k] + ub(pp[k], 1) * cb[2 * k]) * g0 * sigm(g0);
;                 const float y1 = (bfhi(h[k]) + ub(pp[k], 2) * cf[2 * k + 1] + ub(pp[k], 3) * cb[2 * k + 1]) * g1 * sigm(g1);
;                 o[k] = cvtpk(y0, y1);
;             }
;             *(u32x4*)(ZG + off) = o;
	v_lshlrev_b32_e32 v72, 16, v54
	v_and_b32_e32 v73, 0xffff0000, v54
	v_lshlrev_b32_e32 v80, 16, v58
	v_and_b32_e32 v81, 0xffff0000, v58
	v_cvt_f32_ubyte0_e32 v88, v62
	v_cvt_f32_ubyte2_e32 v89, v62
	v_cvt_f32_ubyte1_e32 v96, v62
	v_cvt_f32_ubyte3_e32 v97, v62
	v_lshlrev_b32_e32 v74, 16, v55
	v_and_b32_e32 v75, 0xffff0000, v55
	v_lshlrev_b32_e32 v82, 16, v59
	v_and_b32_e32 v83, 0xffff0000, v59
	v_cvt_f32_ubyte0_e32 v90, v63
	v_cvt_f32_ubyte2_e32 v91, v63
	v_cvt_f32_ubyte1_e32 v98, v63
	v_cvt_f32_ubyte3_e32 v99, v63
	v_lshlrev_b32_e32 v76, 16, v56
	v_and_b32_e32 v77, 0xffff0000, v56
	v_lshlrev_b32_e32 v84, 16, v60
	v_and_b32_e32 v85, 0xffff0000, v60
	v_cvt_f32_ubyte0_e32 v92, v64
	v_cvt_f32_ubyte2_e32 v93, v64
	v_cvt_f32_ubyte1_e32 v100, v64
	v_cvt_f32_ubyte3_e32 v101, v64
	v_lshlrev_b32_e32 v78, 16, v57
	v_and_b32_e32 v79, 0xffff0000, v57
	v_lshlrev_b32_e32 v86, 16, v61
	v_and_b32_e32 v87, 0xffff0000, v61
	v_cvt_f32_ubyte0_e32 v94, v65
	v_cvt_f32_ubyte2_e32 v95, v65
	v_cvt_f32_ubyte1_e32 v102, v65
	v_cvt_f32_ubyte3_e32 v103, v65
	v_pk_mul_f32 v[104:105], v[72:73], s[40:41] op_sel_hi:[1,0]
	v_pk_mul_f32 v[106:107], v[74:75], s[40:41] op_sel_hi:[1,0]
	v_pk_mul_f32 v[108:109], v[76:77], s[40:41] op_sel_hi:[1,0]
	v_pk_mul_f32 v[110:111], v[78:79], s[40:41] op_sel_hi:[1,0]
	v_pk_fma_f32 v[80:81], v[88:89], v[18:19], v[80:81]
	v_pk_fma_f32 v[82:83], v[90:91], v[20:21], v[82:83]
	v_pk_fma_f32 v[84:85], v[92:93], v[14:15], v[84:85]
	v_pk_fma_f32 v[86:87], v[94:95], v[16:17], v[86:87]
	v_exp_f32_e32 v104, v104
	v_exp_f32_e32 v105, v105
	v_exp_f32_e32 v106, v106
	v_exp_f32_e32 v107, v107
	v_exp_f32_e32 v108, v108
	v_exp_f32_e32 v109, v109
	v_exp_f32_e32 v110, v110
	v_exp_f32_e32 v111, v111
	v_pk_fma_f32 v[80:81], v[96:97], v[2:3], v[80:81]
	v_pk_fma_f32 v[82:83], v[98:99], v[4:5], v[82:83]
	v_pk_fma_f32 v[84:85], v[100:101], v[6:7], v[84:85]
	v_pk_fma_f32 v[86:87], v[102:103], v[8:9], v[86:87]
	v_pk_add_f32 v[104:105], v[104:105], 1.0 op_sel_hi:[1,0]
	v_pk_add_f32 v[106:107], v[106:107], 1.0 op_sel_hi:[1,0]
	v_pk_add_f32 v[108:109], v[108:109], 1.0 op_sel_hi:[1,0]
	v_pk_add_f32 v[110:111], v[110:111], 1.0 op_sel_hi:[1,0]
	v_rcp_f32_e32 v104, v104
	v_rcp_f32_e32 v105, v105
	v_rcp_f32_e32 v106, v106
	v_rcp_f32_e32 v107, v107
	v_rcp_f32_e32 v108, v108
	v_rcp_f32_e32 v109, v109
	v_rcp_f32_e32 v110, v110
	v_rcp_f32_e32 v111, v111
	v_pk_mul_f32 v[80:81], v[80:81], v[72:73]
	v_pk_mul_f32 v[82:83], v[82:83], v[74:75]
	v_pk_mul_f32 v[84:85], v[84:85], v[76:77]
	v_pk_mul_f32 v[86:87], v[86:87], v[78:79]
	v_pk_mul_f32 v[80:81], v[104:105], v[80:81]
	v_pk_mul_f32 v[82:83], v[106:107], v[82:83]
	v_pk_mul_f32 v[84:85], v[108:109], v[84:85]
	v_pk_mul_f32 v[86:87], v[110:111], v[86:87]
	v_cvt_pk_bf16_f32 v66, v80, v81
	v_cvt_pk_bf16_f32 v67, v82, v83
	v_cvt_pk_bf16_f32 v68, v84, v85
	v_cvt_pk_bf16_f32 v69, v86, v87
	global_store_dwordx4 v71, v[66:69], s[10:11]
	s_waitcnt vmcnt(5)
	v_lshlrev_b32_e32 v72, 16, v112
	v_and_b32_e32 v73, 0xffff0000, v112
	v_lshlrev_b32_e32 v80, 16, v116
	v_and_b32_e32 v81, 0xffff0000, v116
	v_cvt_f32_ubyte0_e32 v88, v120
	v_cvt_f32_ubyte2_e32 v89, v120
	v_cvt_f32_ubyte1_e32 v96, v120
	v_cvt_f32_ubyte3_e32 v97, v120
	v_lshlrev_b32_e32 v74, 16, v113
	v_and_b32_e32 v75, 0xffff0000, v113
	v_lshlrev_b32_e32 v82, 16, v117
	v_and_b32_e32 v83, 0xffff0000, v117
	v_cvt_f32_ubyte0_e32 v90, v121
	v_cvt_f32_ubyte2_e32 v91, v121
	v_cvt_f32_ubyte1_e32 v98, v121
	v_cvt_f32_ubyte3_e32 v99, v121
	v_lshlrev_b32_e32 v76, 16, v114
	v_and_b32_e32 v77, 0xffff0000, v114
	v_lshlrev_b32_e32 v84, 16, v118
	v_and_b32_e32 v85, 0xffff0000, v118
	v_cvt_f32_ubyte0_e32 v92, v122
	v_cvt_f32_ubyte2_e32 v93, v122
	v_cvt_f32_ubyte1_e32 v100, v122
	v_cvt_f32_ubyte3_e32 v101, v122
	v_lshlrev_b32_e32 v78, 16, v115
	v_and_b32_e32 v79, 0xffff0000, v115
	v_lshlrev_b32_e32 v86, 16, v119
	v_and_b32_e32 v87, 0xffff0000, v119
	v_cvt_f32_ubyte0_e32 v94, v123
	v_cvt_f32_ubyte2_e32 v95, v123
	v_cvt_f32_ubyte1_e32 v102, v123
	v_cvt_f32_ubyte3_e32 v103, v123
	v_pk_mul_f32 v[104:105], v[72:73], s[40:41] op_sel_hi:[1,0]
	v_pk_mul_f32 v[106:107], v[74:75], s[40:41] op_sel_hi:[1,0]
	v_pk_mul_f32 v[108:109], v[76:77], s[40:41] op_sel_hi:[1,0]
	v_pk_mul_f32 v[110:111], v[78:79], s[40:41] op_sel_hi:[1,0]
	v_pk_fma_f32 v[80:81], v[88:89], v[18:19], v[80:81]
	v_pk_fma_f32 v[82:83], v[90:91], v[20:21], v[82:83]
	v_pk_fma_f32 v[84:85], v[92:93], v[14:15], v[84:85]
	v_pk_fma_f32 v[86:87], v[94:95], v[16:17], v[86:87]
	v_exp_f32_e32 v104, v104
	v_exp_f32_e32 v105, v105
	v_exp_f32_e32 v106, v106
	v_exp_f32_e32 v107, v107
	v_exp_f32_e32 v108, v108
	v_exp_f32_e32 v109, v109
	v_exp_f32_e32 v110, v110
	v_exp_f32_e32 v111, v111
	v_pk_fma_f32 v[80:81], v[96:97], v[2:3], v[80:81]
	v_pk_fma_f32 v[82:83], v[98:99], v[4:5], v[82:83]
	v_pk_fma_f32 v[84:85], v[100:101], v[6:7], v[84:85]
	v_pk_fma_f32 v[86:87], v[102:103], v[8:9], v[86:87]
	v_pk_add_f32 v[104:105], v[104:105], 1.0 op_sel_hi:[1,0]
	v_pk_add_f32 v[106:107], v[106:107], 1.0 op_sel_hi:[1,0]
	v_pk_add_f32 v[108:109], v[108:109], 1.0 op_sel_hi:[1,0]
	v_pk_add_f32 v[110:111], v[110:111], 1.0 op_sel_hi:[1,0]
	v_rcp_f32_e32 v104, v104
	v_rcp_f32_e32 v105, v105
	v_rcp_f32_e32 v106, v106
	v_rcp_f32_e32 v107, v107
	v_rcp_f32_e32 v108, v108
	v_rcp_f32_e32 v109, v109
	v_rcp_f32_e32 v110, v110
	v_rcp_f32_e32 v111, v111
	v_pk_mul_f32 v[80:81], v[80:81], v[72:73]
	v_pk_mul_f32 v[82:83], v[82:83], v[74:75]
	v_pk_mul_f32 v[84:85], v[84:85], v[76:77]
	v_pk_mul_f32 v[86:87], v[86:87], v[78:79]
	v_pk_mul_f32 v[80:81], v[104:105], v[80:81]
	v_pk_mul_f32 v[82:83], v[106:107], v[82:83]
	v_pk_mul_f32 v[84:85], v[108:109], v[84:85]
	v_pk_mul_f32 v[86:87], v[110:111], v[86:87]
	v_cvt_pk_bf16_f32 v124, v80, v81
	v_cvt_pk_bf16_f32 v125, v82, v83
	v_cvt_pk_bf16_f32 v126, v84, v85
	v_cvt_pk_bf16_f32 v127, v86, v87
	global_store_dwordx4 v128, v[124:127], s[10:11]
	s_waitcnt vmcnt(2)
; DI unsigned cvtpk(float lo, float hi) { unsigned r; asm volatile("v_cvt_pk_bf16_f32 %0, %1, %2" : "=v"(r) : "v"(lo), "v"(hi)); return r; }
; DI float bflo(unsigned w) { return __uint_as_float(w << 16); }
; DI float bfhi(unsigned w) { return __uint_as_float(w & 0xffff0000u); }
; DI float sigm(float x) { return rcpf_(1.f + ex2(-x * LOG2E)); }
; DI float ub(unsigned w, int i) { return (float)((w >> (8 * i)) & 0xffu); }
; DI void phase_fixup(const Params& p) {
;     ...
;     for (int it = blockIdx.x; it < 512; it += gridDim.x) {
;     ...
;         for (int i = 0; i < 16; ++i) {
;             const size_t off = (size_t)(c * 128 + rq * 32 + 2 * i + r2) * 2048 + ch;
;             const u32x4 g = __builtin_nontemporal_load((const u32x4*)(ZG + off)), h = __builtin_nontemporal_load((const u32x4*)(HLp + off)), pp = __builtin_nontemporal_load((const u32x4*)(PPp + off));
;             u32x4 o;
; #pragma unroll
;             for (int k = 0; k < 4; ++k) {
;                 const float g0 = bflo(g[k]), g1 = bfhi(g[k]);
;                 const float y0 = (bflo(h[k]) + ub(pp[k], 0) * cf[2 * k] + ub(pp[k], 1) * cb[2 * k]) * g0 * sigm(g0);
;                 const float y1 = (bfhi(h[k]) + ub(pp[k], 2) * cf[2 * k + 1] + ub(pp[k], 3) * cb[2 * k + 1]) * g1 * sigm(g1);
;                 o[k] = cvtpk(y0, y1);
;             }
;             *(u32x4*)(ZG + off) = o;
;         }
	v_lshlrev_b32_e32 v72, 16, v132
	v_and_b32_e32 v73, 0xffff0000, v132
	v_lshlrev_b32_e32 v80, 16, v136
	v_and_b32_e32 v81, 0xffff0000, v136
	v_cvt_f32_ubyte0_e32 v88, v140
	v_cvt_f32_ubyte2_e32 v89, v140
	v_cvt_f32_ubyte1_e32 v96, v140
	v_cvt_f32_ubyte3_e32 v97, v140
	v_lshlrev_b32_e32 v74, 16, v133
	v_and_b32_e32 v75, 0xffff0000, v133
	v_lshlrev_b32_e32 v82, 16, v137
	v_and_b32_e32 v83, 0xffff0000, v137
	v_cvt_f32_ubyte0_e32 v90, v141
	v_cvt_f32_ubyte2_e32 v91, v141
	v_cvt_f32_ubyte1_e32 v98, v141
	v_cvt_f32_ubyte3_e32 v99, v141
	v_lshlrev_b32_e32 v76, 16, v134
	v_and_b32_e32 v77, 0xffff0000, v134
	v_lshlrev_b32_e32 v84, 16, v138
	v_and_b32_e32 v85, 0xffff0000, v138
	v_cvt_f32_ubyte0_e32 v92, v142
	v_cvt_f32_ubyte2_e32 v93, v142
	v_cvt_f32_ubyte1_e32 v100, v142
	v_cvt_f32_ubyte3_e32 v101, v142
	v_lshlrev_b32_e32 v78, 16, v135
	v_and_b32_e32 v79, 0xffff0000, v135
	v_lshlrev_b32_e32 v86, 16, v139
	v_and_b32_e32 v87, 0xffff0000, v139
	v_cvt_f32_ubyte0_e32 v94, v143
	v_cvt_f32_ubyte2_e32 v95, v143
	v_cvt_f32_ubyte1_e32 v102, v143
	v_cvt_f32_ubyte3_e32 v103, v143
	v_pk_mul_f32 v[104:105], v[72:73], s[40:41] op_sel_hi:[1,0]
	v_pk_mul_f32 v[106:107], v[74:75], s[40:41] op_sel_hi:[1,0]
	v_pk_mul_f32 v[108:109], v[76:77], s[40:41] op_sel_hi:[1,0]
	v_pk_mul_f32 v[110:111], v[78:79], s[40:41] op_sel_hi:[1,0]
	v_pk_fma_f32 v[80:81], v[88:89], v[18:19], v[80:81]
	v_pk_fma_f32 v[82:83], v[90:91], v[20:21], v[82:83]
	v_pk_fma_f32 v[84:85], v[92:93], v[14:15], v[84:85]
	v_pk_fma_f32 v[86:87], v[94:95], v[16:17], v[86:87]
	v_exp_f32_e32 v104, v104
	v_exp_f32_e32 v105, v105
	v_exp_f32_e32 v106, v106
	v_exp_f32_e32 v107, v107
	v_exp_f32_e32 v108, v108
	v_exp_f32_e32 v109, v109
	v_exp_f32_e32 v110, v110
	v_exp_f32_e32 v111, v111
	v_pk_fma_f32 v[80:81], v[96:97], v[2:3], v[80:81]
	v_pk_fma_f32 v[82:83], v[98:99], v[4:5], v[82:83]
	v_pk_fma_f32 v[84:85], v[100:101], v[6:7], v[84:85]
	v_pk_fma_f32 v[86:87], v[102:103], v[8:9], v[86:87]
	v_pk_add_f32 v[104:105], v[104:105], 1.0 op_sel_hi:[1,0]
	v_pk_add_f32 v[106:107], v[106:107], 1.0 op_sel_hi:[1,0]
	v_pk_add_f32 v[108:109], v[108:109], 1.0 op_sel_hi:[1,0]
	v_pk_add_f32 v[110:111], v[110:111], 1.0 op_sel_hi:[1,0]
	v_rcp_f32_e32 v104, v104
	v_rcp_f32_e32 v105, v105
	v_rcp_f32_e32 v106, v106
	v_rcp_f32_e32 v107, v107
	v_rcp_f32_e32 v108, v108
	v_rcp_f32_e32 v109, v109
	v_rcp_f32_e32 v110, v110
	v_rcp_f32_e32 v111, v111
	v_pk_mul_f32 v[80:81], v[80:81], v[72:73]
	v_pk_mul_f32 v[82:83], v[82:83], v[74:75]
	v_pk_mul_f32 v[84:85], v[84:85], v[76:77]
	v_pk_mul_f32 v[86:87], v[86:87], v[78:79]
	v_pk_mul_f32 v[80:81], v[104:105], v[80:81]
	v_pk_mul_f32 v[82:83], v[106:107], v[82:83]
	v_pk_mul_f32 v[84:85], v[108:109], v[84:85]
	v_pk_mul_f32 v[86:87], v[110:111], v[86:87]
	v_cvt_pk_bf16_f32 v144, v80, v81
	v_cvt_pk_bf16_f32 v145, v82, v83
	v_cvt_pk_bf16_f32 v146, v84, v85
	v_cvt_pk_bf16_f32 v147, v86, v87
	global_store_dwordx4 v129, v[144:147], s[10:11]
	s_add_i32 s17, s17, s24
	s_add_i32 s15, s15, s16
	s_cmpk_gt_i32 s17, 0x1ff
	s_cbranch_scc0 .LBB0_377
	s_load_dwordx2 s[4:5], s[0:1], 0xc8
	s_waitcnt lgkmcnt(0)
	v_mov_b64_e32 v[0:1], s[4:5]
